# rw_prepass: hoisted prev-token loads, no vmcnt(0) drains on prompt path in per-token part
# speedup vs baseline: 1.0023x; 1.0023x over previous
.LBB0_175:
	s_add_i32 s0, s34, 0x4000
	s_mul_i32 s10, s0, 0x2600
	s_add_u32 s12, s14, s10
	v_readlane_b32 s10, v251, 21
	s_mul_hi_i32 s1, s0, 0x2600
	v_readlane_b32 s11, v251, 22
	s_addc_u32 s1, s15, s1
	s_lshl_b64 s[10:11], s[10:11], 1
	s_add_u32 s10, s12, s10
	s_addc_u32 s11, s1, s11
	v_lshl_add_u64 v[2:3], v[78:79], 1, s[10:11]
	s_movk_i32 s1, 0x1000
	v_add_co_u32_e32 v4, vcc, s1, v2
	s_movk_i32 s1, 0x3000
	s_nop 0
	v_addc_co_u32_e32 v5, vcc, 0, v3, vcc
	v_add_co_u32_e32 v6, vcc, s1, v2
	s_movk_i32 s12, 0x4000
	s_nop 0
	v_addc_co_u32_e32 v7, vcc, 0, v3, vcc
	v_add_co_u32_e32 v8, vcc, s12, v2
	s_movk_i32 s1, 0x6000
	s_nop 0
	v_addc_co_u32_e32 v9, vcc, 0, v3, vcc
	v_add_co_u32_e32 v10, vcc, s1, v2
	s_mov_b32 s1, 0x8000
	s_nop 0
	v_addc_co_u32_e32 v11, vcc, 0, v3, vcc
	v_add_co_u32_e32 v12, vcc, s1, v2
	s_mov_b64 s[10:11], 0x1800
	s_nop 0
	v_addc_co_u32_e32 v13, vcc, 0, v3, vcc
	s_mov_b32 s1, 0xb000
	v_lshl_add_u64 v[126:127], v[2:3], 0, s[10:11]
	global_load_ushort v219, v[4:5], off offset:2048
	global_load_ushort v217, v[6:7], off offset:3584
	global_load_ushort v218, v[8:9], off offset:512
	global_load_ushort v215, v[10:11], off offset:1024
	global_load_ushort v216, v[10:11], off offset:2048
	global_load_ushort v213, v[12:13], off offset:2560
	global_load_ushort v214, v[12:13], off offset:3584
	global_load_ushort v220, v[126:127], off offset:1024
	v_add_co_u32_e32 v4, vcc, s1, v2
	s_mov_b32 s1, 0xd000
	s_nop 0
	v_addc_co_u32_e32 v5, vcc, 0, v3, vcc
	v_add_co_u32_e32 v6, vcc, s1, v2
	s_mov_b32 s1, 0xf000
	s_nop 0
	v_addc_co_u32_e32 v7, vcc, 0, v3, vcc
	v_add_co_u32_e32 v8, vcc, s1, v2
	s_mov_b32 s1, 0x10000
	s_nop 0
	v_addc_co_u32_e32 v9, vcc, 0, v3, vcc
	v_add_co_u32_e32 v10, vcc, s1, v2
	s_mov_b32 s1, 0x12000
	s_nop 0
	v_addc_co_u32_e32 v11, vcc, 0, v3, vcc
	v_add_co_u32_e32 v12, vcc, s1, v2
	s_mov_b32 s1, 0x14000
	s_nop 0
	v_addc_co_u32_e32 v13, vcc, 0, v3, vcc
	global_load_ushort v211, v[4:5], off
	global_load_ushort v212, v[4:5], off offset:1024
	global_load_ushort v209, v[6:7], off offset:1536
	global_load_ushort v210, v[6:7], off offset:2560
	global_load_ushort v207, v[8:9], off offset:3072
	global_load_ushort v208, v[10:11], off
	global_load_ushort v205, v[12:13], off offset:512
	global_load_ushort v206, v[12:13], off offset:1536
	v_add_co_u32_e32 v4, vcc, s1, v2
	s_mov_b32 s1, 0x16000
	s_nop 0
	v_addc_co_u32_e32 v5, vcc, 0, v3, vcc
	v_add_co_u32_e32 v6, vcc, s1, v2
	s_mov_b32 s1, 0x17000
	s_nop 0
	v_addc_co_u32_e32 v7, vcc, 0, v3, vcc
	v_add_co_u32_e32 v8, vcc, s1, v2
	s_mov_b32 s1, 0x19000
	s_nop 0
	v_addc_co_u32_e32 v9, vcc, 0, v3, vcc
	v_add_co_u32_e32 v10, vcc, s1, v2
	s_mov_b32 s1, 0x1b000
	s_nop 0
	v_addc_co_u32_e32 v11, vcc, 0, v3, vcc
	v_add_co_u32_e32 v12, vcc, s1, v2
	s_mov_b32 s1, 0x1e000
	s_nop 0
	v_addc_co_u32_e32 v13, vcc, 0, v3, vcc
	global_load_ushort v203, v[4:5], off offset:2048
	global_load_ushort v204, v[4:5], off offset:3072
	global_load_ushort v201, v[6:7], off offset:3584
	global_load_ushort v202, v[8:9], off offset:512
	global_load_ushort v199, v[10:11], off offset:1024
	global_load_ushort v200, v[10:11], off offset:2048
	global_load_ushort v197, v[12:13], off offset:2560
	global_load_ushort v198, v[12:13], off offset:3584
	v_add_co_u32_e32 v4, vcc, s1, v2
	s_mov_b32 s1, 0x20000
	s_nop 0
	v_addc_co_u32_e32 v5, vcc, 0, v3, vcc
	v_add_co_u32_e32 v6, vcc, s1, v2
	s_mov_b32 s1, 0x22000
	s_nop 0
	v_addc_co_u32_e32 v7, vcc, 0, v3, vcc
	v_add_co_u32_e32 v8, vcc, s1, v2
	s_mov_b32 s1, 0x23000
	s_nop 0
	v_addc_co_u32_e32 v9, vcc, 0, v3, vcc
	v_add_co_u32_e32 v10, vcc, s1, v2
	s_mov_b32 s1, 0x25000
	s_nop 0
	v_addc_co_u32_e32 v11, vcc, 0, v3, vcc
	v_add_co_u32_e32 v2, vcc, s1, v2
	v_lshlrev_b32_e32 v0, 1, v80
	s_nop 0
	v_addc_co_u32_e32 v3, vcc, 0, v3, vcc
	global_load_ushort v195, v[4:5], off
	global_load_ushort v196, v[4:5], off offset:1024
	global_load_ushort v193, v[6:7], off offset:1536
	global_load_ushort v194, v[6:7], off offset:2560
	global_load_ushort v191, v[8:9], off offset:3072
	global_load_ushort v192, v[10:11], off
	global_load_ushort v189, v[2:3], off offset:512
	global_load_ushort v190, v[2:3], off offset:1536
	s_cmpk_gt_i32 s35, 0x1ff
	s_cbranch_scc1 .Lrwp_prev_skip
	s_and_b32 s98, s35, 63
	s_cmp_eq_u32 s98, 0
	s_cbranch_scc1 .Lrwp_prev_skip
	v_add_co_u32_e32 v244, vcc, 0xffffe000, v126
	s_nop 1
	v_addc_co_u32_e32 v245, vcc, -1, v127, vcc
	global_load_ushort v242, v[244:245], off offset:-1536
	global_load_ushort v243, v[244:245], off offset:-512
.Lrwp_prev_skip:
	v_add_u32_e32 v8, s34, v152
	v_add_u32_e32 v9, 0x4000, v8
	v_mov_b64_e32 v[2:3], s[14:15]
	v_mad_i64_i32 v[2:3], s[10:11], v9, s79, v[2:3]
	v_lshl_add_u64 v[2:3], v[2:3], 0, v[0:1]
	v_add_co_u32_e32 v4, vcc, 0x2000, v2
	s_nop 1
	v_addc_co_u32_e32 v5, vcc, 0, v3, vcc
	s_barrier
	global_load_dwordx2 v[10:11], v[4:5], off offset:1024
	v_and_b32_e32 v0, 0x7ff, v9
	v_cmp_gt_i32_e32 vcc, s12, v9
	s_mov_b64 s[10:11], 0x2400
	s_movk_i32 s1, 0x3fff
	v_cndmask_b32_e32 v0, v153, v0, vcc
	v_lshl_add_u64 v[6:7], v[2:3], 0, s[10:11]
	v_cmp_ne_u32_e64 s[12:13], 0, v0
	v_cmp_lt_i32_e64 s[10:11], s1, v9
	s_and_saveexec_b64 s[24:25], s[12:13]
	s_xor_b64 s[24:25], exec, s[24:25]
	s_cbranch_execz .LBB0_177
	v_add_co_u32_e32 v2, vcc, 0xffffe000, v6
	s_nop 1
	v_addc_co_u32_e32 v3, vcc, -1, v7, vcc
	global_load_dwordx2 v[4:5], v[2:3], off offset:-1536
	s_waitcnt vmcnt(0)
	v_lshlrev_b32_e32 v2, 16, v4
	v_and_b32_e32 v3, 0xffff0000, v4
	v_lshlrev_b32_e32 v4, 16, v5
	v_and_b32_e32 v5, 0xffff0000, v5

.LBB0_231:
	s_or_b64 exec, exec, s[10:11]
	s_waitcnt lgkmcnt(0)
	s_barrier
	global_load_dwordx4 v[54:57], v[90:91], off
	global_load_dwordx4 v[50:53], v[90:91], off offset:64
	global_load_dwordx4 v[42:45], v[86:87], off
	global_load_dwordx4 v[38:41], v[88:89], off
	global_load_dwordx4 v[46:49], v[86:87], off offset:64
	global_load_dwordx4 v[34:37], v[88:89], off offset:64
	global_load_dwordx4 v[58:61], v[90:91], off offset:128
	global_load_dword v146, v[92:93], off
	global_load_dword v76, v[94:95], off
	global_load_dwordx4 v[62:65], v[90:91], off offset:192
	global_load_dwordx4 v[14:17], v[100:101], off
	global_load_dwordx4 v[10:13], v[100:101], off offset:64
	global_load_dwordx4 v[6:9], v[102:103], off
	global_load_dwordx4 v[2:5], v[102:103], off offset:64
	global_load_dword v222, v[104:105], off offset:64
	global_load_dword v221, v[106:107], off offset:64
	ds_read_b128 v[66:69], v161 offset:9216
	global_load_dwordx4 v[18:21], v[108:109], off offset:192
	global_load_dwordx4 v[22:25], v[108:109], off offset:128
	global_load_dwordx4 v[26:29], v[108:109], off offset:64
	global_load_dwordx4 v[30:33], v[108:109], off
	ds_read_b128 v[70:73], v161 offset:9280
	ds_read_b128 v[128:131], v159
	ds_read_b128 v[134:137], v159 offset:64
	ds_read_b128 v[142:145], v159 offset:4608
	ds_read_b128 v[224:227], v159 offset:4672
	v_add_u32_e32 v77, s34, v154
	ds_read_b128 v[228:231], v161 offset:9344
	ds_read_b128 v[232:235], v161 offset:9408
	v_add_u32_e32 v74, 0x4001, v77
	v_ashrrev_i32_e32 v75, 31, v74
	v_add_u32_e32 v0, v155, v160
	s_cmpk_gt_i32 s35, 0x1ff
	s_waitcnt vmcnt(19) lgkmcnt(7)
	v_mfma_f32_16x16x32_bf16 v[66:69], v[66:69], v[54:57], 0
	s_waitcnt vmcnt(18) lgkmcnt(6)
	v_mfma_f32_16x16x32_bf16 v[236:239], v[70:73], v[50:53], v[66:69]
	v_add_u32_e32 v72, 0x4000, v77
	v_add_u32_e32 v70, 0x4010, v77
	v_ashrrev_i32_e32 v73, 31, v72
	s_waitcnt vmcnt(17) lgkmcnt(5)
	v_mfma_f32_16x16x32_bf16 v[66:69], v[128:131], v[42:45], 0
	v_ashrrev_i32_e32 v71, 31, v70
	v_lshlrev_b64 v[132:133], 9, v[72:73]
	v_lshlrev_b64 v[130:131], 9, v[74:75]
	s_waitcnt vmcnt(16) lgkmcnt(3)
	v_mfma_f32_16x16x32_bf16 v[142:145], v[142:145], v[38:41], 0
	v_lshlrev_b64 v[128:129], 9, v[70:71]
	v_lshl_add_u64 v[240:241], v[130:131], 0, v[84:85]
	s_waitcnt vmcnt(15)
	v_mfma_f32_16x16x32_bf16 v[72:75], v[134:137], v[46:49], v[66:69]
	s_waitcnt vmcnt(14) lgkmcnt(2)
	v_mfma_f32_16x16x32_bf16 v[68:71], v[224:227], v[34:37], v[142:145]
	s_nop 0
	v_lshl_add_u64 v[66:67], v[132:133], 0, v[84:85]
	v_lshlrev_b64 v[66:67], 1, v[66:67]
	s_waitcnt vmcnt(12)
	s_nop 1
	v_add_f32_e32 v72, v146, v72
	s_waitcnt lgkmcnt(1)
	v_mfma_f32_16x16x32_bf16 v[134:137], v[228:231], v[58:61], v[236:239]
	v_lshl_add_u64 v[142:143], s[16:17], 0, v[66:67]
	v_lshl_add_u64 v[144:145], s[18:19], 0, v[66:67]
	v_lshl_add_u64 v[224:225], s[20:21], 0, v[66:67]
	s_waitcnt vmcnt(11)
	v_add_f32_e32 v147, v76, v68
	v_add_f32_e32 v223, v76, v69
	s_waitcnt vmcnt(10) lgkmcnt(0)
	v_mfma_f32_16x16x32_bf16 v[66:69], v[232:235], v[62:65], v[134:137]
	v_add_f32_e32 v73, v146, v73
	v_add_f32_e32 v70, v76, v70
	v_mul_f32_e32 v70, 0xbfb8aa3b, v70
	v_max_f32_e64 v134, -v72, 0
	v_mul_f32_e64 v72, |v72|, s82
	v_exp_f32_e32 v72, v72
	v_mul_f32_e32 v135, 0xbfb8aa3b, v147
	v_max_f32_e64 v136, -v73, 0
	v_mul_f32_e64 v73, |v73|, s82
	v_exp_f32_e32 v135, v135
	v_exp_f32_e32 v73, v73
	v_add_f32_e32 v72, 1.0, v72
	v_cmp_gt_f32_e32 vcc, s74, v72
	v_mul_f32_e32 v137, 0xbfb8aa3b, v223
	v_add_f32_e32 v135, 1.0, v135
	v_add_f32_e32 v73, 1.0, v73
	v_cndmask_b32_e64 v147, 0, 32, vcc
	v_bfe_u32 v223, v66, 16, 1
	v_rcp_f32_e32 v135, v135
	v_cmp_gt_f32_e64 s[10:11], s74, v73
	v_add3_u32 v66, v66, v223, s78
	v_ldexp_f32 v72, v72, v147
	global_store_short_d16_hi v[224:225], v66, off
	v_cndmask_b32_e64 v66, 0, 32, s[10:11]
	v_log_f32_e32 v72, v72
	v_ldexp_f32 v66, v73, v66
	v_log_f32_e32 v66, v66
	v_bfe_u32 v73, v135, 16, 1
	v_add3_u32 v73, v135, v73, s78
	v_mul_f32_e32 v135, 0x3f317217, v72
	v_fma_f32 v135, v72, s83, -v135
	global_store_short_d16_hi v[144:145], v73, off
	v_mul_f32_e32 v144, 0x3f317217, v66
	v_fmac_f32_e32 v135, 0x3377d1cf, v72
	v_cndmask_b32_e32 v223, 0, v176, vcc
	v_cmp_lt_f32_e64 vcc, |v72|, s92
	v_fma_f32 v144, v66, s83, -v144
	v_fmac_f32_e32 v135, 0x3f317217, v72
	v_fmac_f32_e32 v144, 0x3377d1cf, v66
	v_cndmask_b32_e32 v72, v72, v135, vcc
	v_cndmask_b32_e64 v224, 0, v176, s[10:11]
	v_cmp_lt_f32_e64 s[10:11], |v66|, s92
	v_fmac_f32_e32 v144, 0x3f317217, v66
	v_sub_f32_e32 v72, v72, v223
	v_cndmask_b32_e64 v66, v66, v144, s[10:11]
	v_add_f32_e32 v72, v134, v72
	v_sub_f32_e32 v66, v66, v224
	v_sub_f32_e32 v72, -0.5, v72
	v_add_f32_e32 v66, v136, v66
	v_mul_f32_e32 v72, 0x3fb8aa3b, v72
	v_sub_f32_e32 v66, -0.5, v66
	v_exp_f32_e32 v72, v72
	v_mul_f32_e32 v66, 0x3fb8aa3b, v66
	v_exp_f32_e32 v66, v66
	v_exp_f32_e32 v137, v137
	v_and_b32_e32 v73, 0xffff0000, v73
	v_xor_b32_e32 v72, 0x80000000, v72
	ds_write_b32 v0, v73 offset:17920
	v_bfe_u32 v73, v72, 16, 1
	v_xor_b32_e32 v66, 0x80000000, v66
	v_add3_u32 v72, v72, v73, s78
	global_store_short_d16_hi v[142:143], v72, off
	v_bfe_u32 v72, v66, 16, 1
	v_add3_u32 v66, v66, v72, s78
	v_add_f32_e32 v72, 1.0, v137
	v_rcp_f32_e32 v136, v72
	v_lshlrev_b64 v[72:73], 1, v[240:241]
	v_lshl_add_u64 v[134:135], s[16:17], 0, v[72:73]
	global_store_short_d16_hi v[134:135], v66, off
	v_bfe_u32 v66, v136, 16, 1
	v_add3_u32 v66, v136, v66, s78
	v_lshl_add_u64 v[134:135], s[18:19], 0, v[72:73]
	global_store_short_d16_hi v[134:135], v66, off
	v_and_b32_e32 v66, 0xffff0000, v66
	ds_write_b32 v182, v66 offset:17920
	v_bfe_u32 v66, v67, 16, 1
	v_add3_u32 v134, v67, v66, s78
	v_lshl_add_u64 v[66:67], s[20:21], 0, v[72:73]
	v_add_f32_e32 v72, v146, v74
	v_mul_f32_e64 v73, |v72|, s82
	v_exp_f32_e32 v73, v73
	v_max_f32_e64 v72, -v72, 0
	v_exp_f32_e32 v70, v70
	global_store_short_d16_hi v[66:67], v134, off
	v_add_f32_e32 v73, 1.0, v73
	v_cmp_gt_f32_e32 vcc, s74, v73
	v_add_u32_e32 v66, 0x4002, v77
	v_ashrrev_i32_e32 v67, 31, v66
	v_cndmask_b32_e64 v74, 0, 32, vcc
	v_ldexp_f32 v73, v73, v74
	v_log_f32_e32 v73, v73
	v_add_f32_e32 v70, 1.0, v70
	v_lshlrev_b64 v[136:137], 9, v[66:67]
	v_rcp_f32_e32 v70, v70
	v_mul_f32_e32 v74, 0x3f317217, v73
	v_fma_f32 v74, v73, s83, -v74
	v_fmac_f32_e32 v74, 0x3377d1cf, v73
	v_fmac_f32_e32 v74, 0x3f317217, v73
	v_cmp_lt_f32_e64 s[10:11], |v73|, s92
	v_lshl_add_u64 v[66:67], v[136:137], 0, v[84:85]
	v_lshlrev_b64 v[66:67], 1, v[66:67]
	v_cndmask_b32_e64 v73, v73, v74, s[10:11]
	v_cndmask_b32_e32 v74, 0, v176, vcc
	v_sub_f32_e32 v73, v73, v74
	v_add_f32_e32 v72, v72, v73
	v_sub_f32_e32 v72, -0.5, v72
	v_mul_f32_e32 v72, 0x3fb8aa3b, v72
	v_exp_f32_e32 v72, v72
	s_nop 0
	v_xor_b32_e32 v72, 0x80000000, v72
	v_bfe_u32 v73, v72, 16, 1
	v_add3_u32 v74, v72, v73, s78
	v_lshl_add_u64 v[72:73], s[16:17], 0, v[66:67]
	global_store_short_d16_hi v[72:73], v74, off
	v_bfe_u32 v72, v70, 16, 1
	v_add3_u32 v70, v70, v72, s78
	v_lshl_add_u64 v[72:73], s[18:19], 0, v[66:67]
	global_store_short_d16_hi v[72:73], v70, off
	v_and_b32_e32 v70, 0xffff0000, v70
	ds_write_b32 v183, v70 offset:17920
	v_bfe_u32 v70, v68, 16, 1
	v_add3_u32 v68, v68, v70, s78
	v_add_f32_e32 v70, v146, v75
	v_mul_f32_e64 v72, |v70|, s82
	v_exp_f32_e32 v72, v72
	v_lshl_add_u64 v[66:67], s[20:21], 0, v[66:67]
	global_store_short_d16_hi v[66:67], v68, off
	v_add_u32_e32 v66, 0x4003, v77
	v_add_f32_e32 v67, 1.0, v72
	v_cmp_gt_f32_e32 vcc, s74, v67
	s_nop 1
	v_cndmask_b32_e64 v68, 0, 32, vcc
	v_ldexp_f32 v67, v67, v68
	v_log_f32_e32 v68, v67
	v_ashrrev_i32_e32 v67, 31, v66
	v_lshlrev_b64 v[134:135], 9, v[66:67]
	v_max_f32_e64 v66, -v70, 0
	v_add_f32_e32 v70, v76, v71
	v_mul_f32_e32 v70, 0xbfb8aa3b, v70
	v_exp_f32_e32 v70, v70
	v_mul_f32_e32 v67, 0x3f317217, v68
	v_fma_f32 v67, v68, s83, -v67
	v_fmac_f32_e32 v67, 0x3377d1cf, v68
	v_add_f32_e32 v70, 1.0, v70
	v_rcp_f32_e32 v70, v70
	v_fmac_f32_e32 v67, 0x3f317217, v68
	v_cmp_lt_f32_e64 s[10:11], |v68|, s92
	v_bfe_u32 v71, v70, 16, 1
	v_add3_u32 v74, v70, v71, s78
	v_and_b32_e32 v70, 0xffff0000, v74
	ds_write_b32 v184, v70 offset:17920
	ds_read_b128 v[70:73], v161 offset:13568
	ds_read_b128 v[142:145], v161 offset:13632
	v_cndmask_b32_e64 v67, v68, v67, s[10:11]
	v_cndmask_b32_e32 v68, 0, v176, vcc
	v_sub_f32_e32 v67, v67, v68
	v_add_f32_e32 v66, v66, v67
	ds_read_b128 v[224:227], v161 offset:13696
	v_sub_f32_e32 v66, -0.5, v66
	s_waitcnt lgkmcnt(2)
	v_mfma_f32_16x16x32_bf16 v[54:57], v[70:73], v[54:57], 0
	v_mul_f32_e32 v66, 0x3fb8aa3b, v66
	v_exp_f32_e32 v68, v66
	v_lshl_add_u64 v[66:67], v[134:135], 0, v[84:85]
	s_waitcnt lgkmcnt(1)
	v_mfma_f32_16x16x32_bf16 v[50:53], v[142:145], v[50:53], v[54:57]
	v_lshlrev_b64 v[66:67], 1, v[66:67]
	v_xor_b32_e32 v68, 0x80000000, v68
	v_bfe_u32 v75, v68, 16, 1
	ds_read_b128 v[54:57], v159 offset:2304
	ds_read_b128 v[70:73], v161 offset:13760
	v_add3_u32 v68, v68, v75, s78
	s_waitcnt lgkmcnt(2)
	v_mfma_f32_16x16x32_bf16 v[50:53], v[224:227], v[58:61], v[50:53]
	v_lshl_add_u64 v[58:59], s[16:17], 0, v[66:67]
	global_store_short_d16_hi v[58:59], v68, off
	ds_read_b128 v[58:61], v159 offset:2368
	s_waitcnt lgkmcnt(2)
	v_mfma_f32_16x16x32_bf16 v[42:45], v[54:57], v[42:45], 0
	s_waitcnt lgkmcnt(0)
	v_mfma_f32_16x16x32_bf16 v[42:45], v[58:61], v[46:49], v[42:45]
	v_mfma_f32_16x16x32_bf16 v[50:53], v[70:73], v[62:65], v[50:53]
	s_nop 6
	v_add_f32_e32 v42, v146, v42
	v_mul_f32_e64 v46, |v42|, s82
	v_exp_f32_e32 v48, v46
	v_lshl_add_u64 v[62:63], s[18:19], 0, v[66:67]
	global_store_short_d16_hi v[62:63], v74, off
	v_bfe_u32 v62, v69, 16, 1
	v_add3_u32 v68, v69, v62, s78
	v_lshl_add_u64 v[46:47], s[20:21], 0, v[66:67]
	ds_read_b128 v[54:57], v159 offset:6912
	ds_read_b128 v[62:65], v159 offset:6976
	global_store_short_d16_hi v[46:47], v68, off
	v_add_f32_e32 v46, 1.0, v48
	v_cmp_gt_f32_e32 vcc, s74, v46
	s_waitcnt lgkmcnt(1)
	v_mfma_f32_16x16x32_bf16 v[38:41], v[54:57], v[38:41], 0
	v_cndmask_b32_e64 v47, 0, 32, vcc
	v_ldexp_f32 v46, v46, v47
	v_log_f32_e32 v46, v46
	s_waitcnt lgkmcnt(0)
	v_mfma_f32_16x16x32_bf16 v[34:37], v[62:65], v[34:37], v[38:41]
	v_cmp_lt_f32_e64 s[10:11], |v46|, s92
	s_nop 1
	v_mul_f32_e32 v41, 0x3f317217, v46
	v_fma_f32 v41, v46, s83, -v41
	v_fmac_f32_e32 v41, 0x3377d1cf, v46
	v_fmac_f32_e32 v41, 0x3f317217, v46
	v_max_f32_e64 v40, -v42, 0
	v_cndmask_b32_e64 v41, v46, v41, s[10:11]
	v_cndmask_b32_e32 v42, 0, v176, vcc
	v_sub_f32_e32 v41, v41, v42
	v_add_f32_e32 v34, v76, v34
	v_add_f32_e32 v40, v40, v41
	v_mul_f32_e32 v34, 0xbfb8aa3b, v34
	v_sub_f32_e32 v40, -0.5, v40
	v_exp_f32_e32 v34, v34
	v_mul_f32_e32 v40, 0x3fb8aa3b, v40
	v_exp_f32_e32 v40, v40
	v_lshl_add_u64 v[38:39], v[128:129], 0, v[84:85]
	v_add_f32_e32 v34, 1.0, v34
	v_rcp_f32_e32 v34, v34
	v_xor_b32_e32 v40, 0x80000000, v40
	v_bfe_u32 v41, v40, 16, 1
	v_lshlrev_b64 v[38:39], 1, v[38:39]
	v_add3_u32 v42, v40, v41, s78
	v_lshl_add_u64 v[40:41], s[16:17], 0, v[38:39]
	global_store_short_d16_hi v[40:41], v42, off
	v_bfe_u32 v40, v34, 16, 1
	v_add3_u32 v34, v34, v40, s78
	v_lshl_add_u64 v[40:41], s[18:19], 0, v[38:39]
	global_store_short_d16_hi v[40:41], v34, off
	v_add_f32_e32 v40, v146, v43
	v_mul_f32_e64 v41, |v40|, s82
	v_exp_f32_e32 v41, v41
	v_and_b32_e32 v34, 0xffff0000, v34
	ds_write_b32 v185, v34 offset:17920
	v_bfe_u32 v34, v50, 16, 1
	v_add3_u32 v34, v50, v34, s78
	v_lshl_add_u64 v[38:39], s[20:21], 0, v[38:39]
	global_store_short_d16_hi v[38:39], v34, off
	v_add_f32_e32 v34, 1.0, v41
	v_cmp_gt_f32_e32 vcc, s74, v34
	v_max_f32_e64 v40, -v40, 0
	v_add_f32_e32 v35, v76, v35
	v_cndmask_b32_e64 v41, 0, 32, vcc
	v_ldexp_f32 v34, v34, v41
	v_log_f32_e32 v34, v34
	v_mul_f32_e32 v35, 0xbfb8aa3b, v35
	v_exp_f32_e32 v35, v35
	v_add_u32_e32 v38, 0x4011, v77
	v_mul_f32_e32 v41, 0x3f317217, v34
	v_fma_f32 v41, v34, s83, -v41
	v_fmac_f32_e32 v41, 0x3377d1cf, v34
	v_fmac_f32_e32 v41, 0x3f317217, v34
	v_cmp_lt_f32_e64 s[10:11], |v34|, s92
	v_ashrrev_i32_e32 v39, 31, v38
	v_lshlrev_b64 v[142:143], 9, v[38:39]
	v_cndmask_b32_e64 v34, v34, v41, s[10:11]
	v_cndmask_b32_e32 v41, 0, v176, vcc
	v_sub_f32_e32 v34, v34, v41
	v_add_f32_e32 v34, v40, v34
	v_sub_f32_e32 v34, -0.5, v34
	v_mul_f32_e32 v34, 0x3fb8aa3b, v34
	v_exp_f32_e32 v34, v34
	v_lshl_add_u64 v[38:39], v[142:143], 0, v[84:85]
	v_add_f32_e32 v36, v76, v36
	v_mul_f32_e32 v36, 0xbfb8aa3b, v36
	v_xor_b32_e32 v34, 0x80000000, v34
	v_bfe_u32 v40, v34, 16, 1
	v_add3_u32 v40, v34, v40, s78
	v_add_f32_e32 v34, 1.0, v35
	v_rcp_f32_e32 v41, v34
	v_lshlrev_b64 v[34:35], 1, v[38:39]
	v_lshl_add_u64 v[38:39], s[16:17], 0, v[34:35]
	global_store_short_d16_hi v[38:39], v40, off
	v_bfe_u32 v38, v41, 16, 1
	v_add3_u32 v40, v41, v38, s78
	v_lshl_add_u64 v[38:39], s[18:19], 0, v[34:35]
	global_store_short_d16_hi v[38:39], v40, off
	v_add_f32_e32 v39, v146, v44
	v_and_b32_e32 v38, 0xffff0000, v40
	v_mul_f32_e64 v40, |v39|, s82
	v_exp_f32_e32 v40, v40
	ds_write_b32 v186, v38 offset:17920
	v_bfe_u32 v38, v51, 16, 1
	v_add3_u32 v38, v51, v38, s78
	v_lshl_add_u64 v[34:35], s[20:21], 0, v[34:35]
	global_store_short_d16_hi v[34:35], v38, off
	v_add_f32_e32 v38, 1.0, v40
	v_cmp_gt_f32_e32 vcc, s74, v38
	v_max_f32_e64 v39, -v39, 0
	v_exp_f32_e32 v36, v36
	v_cndmask_b32_e64 v40, 0, 32, vcc
	v_ldexp_f32 v38, v38, v40
	v_log_f32_e32 v38, v38
	v_add_u32_e32 v34, 0x4012, v77
	v_ashrrev_i32_e32 v35, 31, v34
	v_add_f32_e32 v36, 1.0, v36
	v_mul_f32_e32 v40, 0x3f317217, v38
	v_fma_f32 v40, v38, s83, -v40
	v_fmac_f32_e32 v40, 0x3377d1cf, v38
	v_fmac_f32_e32 v40, 0x3f317217, v38
	v_cmp_lt_f32_e64 s[10:11], |v38|, s92
	v_lshlrev_b64 v[144:145], 9, v[34:35]
	v_rcp_f32_e32 v36, v36
	v_cndmask_b32_e64 v38, v38, v40, s[10:11]
	v_cndmask_b32_e32 v40, 0, v176, vcc
	v_sub_f32_e32 v38, v38, v40
	v_add_f32_e32 v38, v39, v38
	v_sub_f32_e32 v38, -0.5, v38
	v_mul_f32_e32 v38, 0x3fb8aa3b, v38
	v_exp_f32_e32 v38, v38
	v_lshl_add_u64 v[34:35], v[144:145], 0, v[84:85]
	v_lshlrev_b64 v[34:35], 1, v[34:35]
	v_xor_b32_e32 v38, 0x80000000, v38
	v_bfe_u32 v39, v38, 16, 1
	v_add3_u32 v40, v38, v39, s78
	v_lshl_add_u64 v[38:39], s[16:17], 0, v[34:35]
	global_store_short_d16_hi v[38:39], v40, off
	v_bfe_u32 v38, v36, 16, 1
	v_add3_u32 v36, v36, v38, s78
	v_lshl_add_u64 v[38:39], s[18:19], 0, v[34:35]
	global_store_short_d16_hi v[38:39], v36, off
	v_add_f32_e32 v38, v146, v45
	v_mul_f32_e64 v39, |v38|, s82
	v_exp_f32_e32 v39, v39
	v_and_b32_e32 v36, 0xffff0000, v36
	ds_write_b32 v187, v36 offset:17920
	v_bfe_u32 v36, v52, 16, 1
	v_add3_u32 v36, v52, v36, s78
	v_lshl_add_u64 v[34:35], s[20:21], 0, v[34:35]
	global_store_short_d16_hi v[34:35], v36, off
	v_add_f32_e32 v36, 1.0, v39
	v_cmp_gt_f32_e32 vcc, s74, v36
	v_add_u32_e32 v34, 0x4013, v77
	v_ashrrev_i32_e32 v35, 31, v34
	v_cndmask_b32_e64 v39, 0, 32, vcc
	v_ldexp_f32 v36, v36, v39
	v_log_f32_e32 v36, v36
	v_lshlrev_b64 v[146:147], 9, v[34:35]
	v_max_f32_e64 v34, -v38, 0
	v_lshl_add_u64 v[42:43], v[146:147], 0, v[84:85]
	v_mul_f32_e32 v35, 0x3f317217, v36
	v_fma_f32 v35, v36, s83, -v35
	v_fmac_f32_e32 v35, 0x3377d1cf, v36
	v_fmac_f32_e32 v35, 0x3f317217, v36
	v_cmp_lt_f32_e64 s[10:11], |v36|, s92
	v_lshlrev_b64 v[54:55], 1, v[42:43]
	v_lshl_add_u64 v[42:43], s[16:17], 0, v[54:55]
	v_cndmask_b32_e64 v35, v36, v35, s[10:11]
	v_add_f32_e32 v36, v76, v37
	v_mul_f32_e32 v36, 0xbfb8aa3b, v36
	v_exp_f32_e32 v36, v36
	v_cndmask_b32_e32 v37, 0, v176, vcc
	v_sub_f32_e32 v35, v35, v37
	v_add_f32_e32 v34, v34, v35
	v_add_f32_e32 v35, 1.0, v36
	v_rcp_f32_e32 v35, v35
	v_sub_f32_e32 v34, -0.5, v34
	v_mul_f32_e32 v34, 0x3fb8aa3b, v34
	v_exp_f32_e32 v38, v34
	v_bfe_u32 v34, v35, 16, 1
	v_add3_u32 v48, v35, v34, s78
	v_and_b32_e32 v34, 0xffff0000, v48
	ds_write_b32 v188, v34 offset:17920
	ds_read_b128 v[34:37], v161 offset:9216
	v_xor_b32_e32 v38, 0x80000000, v38
	v_bfe_u32 v39, v38, 16, 1
	v_add3_u32 v44, v38, v39, s78
	ds_read_b128 v[38:41], v161 offset:9280
	s_waitcnt vmcnt(21) lgkmcnt(1)
	v_mfma_f32_16x16x32_bf16 v[34:37], v[34:37], v[30:33], 0
	ds_read_b128 v[58:61], v159 offset:64
	global_store_short_d16_hi v[42:43], v44, off
	ds_read_b128 v[42:45], v161 offset:9344
	s_waitcnt lgkmcnt(2)
	v_mfma_f32_16x16x32_bf16 v[34:37], v[38:41], v[26:29], v[34:37]
	v_bfe_u32 v38, v53, 16, 1
	v_add3_u32 v40, v53, v38, s78
	ds_read_b128 v[50:53], v159
	s_waitcnt lgkmcnt(0)
	v_mfma_f32_16x16x32_bf16 v[62:65], v[50:53], v[14:17], 0
	v_lshl_add_u64 v[46:47], s[18:19], 0, v[54:55]
	global_store_short_d16_hi v[46:47], v48, off
	ds_read_b128 v[46:49], v161 offset:9408
	v_mfma_f32_16x16x32_bf16 v[74:77], v[58:61], v[10:13], v[62:65]
	v_lshl_add_u64 v[38:39], s[20:21], 0, v[54:55]
	global_store_short_d16_hi v[38:39], v40, off
	v_mfma_f32_16x16x32_bf16 v[34:37], v[42:45], v[22:25], v[34:37]
	s_waitcnt lgkmcnt(0)
	v_mfma_f32_16x16x32_bf16 v[66:69], v[46:49], v[18:21], v[34:37]
	s_nop 2
	v_add_f32_e32 v74, v222, v74
	v_mul_f32_e64 v58, |v74|, s82
	v_exp_f32_e32 v223, v58
	global_load_dwordx4 v[46:49], v[112:113], off
	global_load_dwordx4 v[42:45], v[112:113], off offset:64
	global_load_dwordx4 v[38:41], v[114:115], off
	global_load_dwordx4 v[34:37], v[114:115], off offset:64
	global_load_dwordx4 v[54:57], v[116:117], off offset:128
	global_load_dwordx4 v[50:53], v[116:117], off offset:192
	ds_read_b128 v[70:73], v159 offset:4608
	ds_read_b128 v[224:227], v159 offset:4672
	v_add_f32_e32 v223, 1.0, v223
	v_cmp_gt_f32_e32 vcc, s74, v223
	s_waitcnt lgkmcnt(1)
	v_mfma_f32_16x16x32_bf16 v[70:73], v[70:73], v[6:9], 0
	v_cndmask_b32_e64 v228, 0, 32, vcc
	v_ldexp_f32 v223, v223, v228
	v_log_f32_e32 v223, v223
	s_waitcnt lgkmcnt(0)
	v_mfma_f32_16x16x32_bf16 v[70:73], v[224:227], v[2:5], v[70:73]
	v_max_f32_e64 v74, -v74, 0
	v_lshl_add_u64 v[224:225], v[132:133], 0, v[96:97]
	v_mul_f32_e32 v226, 0x3f317217, v223
	v_fma_f32 v226, v223, s83, -v226
	v_fmac_f32_e32 v226, 0x3377d1cf, v223
	v_fmac_f32_e32 v226, 0x3f317217, v223
	v_cmp_lt_f32_e64 s[10:11], |v223|, s92
	s_nop 0
	v_add_f32_e32 v70, v221, v70
	v_mul_f32_e32 v70, 0xbfb8aa3b, v70
	v_cndmask_b32_e64 v223, v223, v226, s[10:11]
	v_cndmask_b32_e32 v226, 0, v176, vcc
	v_sub_f32_e32 v223, v223, v226
	v_add_f32_e32 v74, v74, v223
	v_sub_f32_e32 v74, -0.5, v74
	v_exp_f32_e32 v70, v70
	v_mul_f32_e32 v74, 0x3fb8aa3b, v74
	v_exp_f32_e32 v74, v74
	v_lshlrev_b64 v[224:225], 1, v[224:225]
	v_add_f32_e32 v70, 1.0, v70
	v_rcp_f32_e32 v70, v70
	v_xor_b32_e32 v74, 0x80000000, v74
	v_bfe_u32 v223, v74, 16, 1
	v_add3_u32 v74, v74, v223, s78
	v_lshl_add_u64 v[226:227], s[16:17], 0, v[224:225]
	global_load_dwordx4 v[58:61], v[116:117], off offset:64
	global_load_dwordx4 v[62:65], v[116:117], off
	s_nop 0
	global_store_short_d16_hi v[226:227], v74, off
	v_bfe_u32 v74, v70, 16, 1
	v_add3_u32 v223, v70, v74, s78
	v_add_f32_e32 v70, v222, v75
	v_lshl_add_u64 v[226:227], s[18:19], 0, v[224:225]
	v_mul_f32_e64 v74, |v70|, s82
	global_store_short_d16_hi v[226:227], v223, off
	v_exp_f32_e32 v226, v74
	v_bfe_u32 v74, v66, 16, 1
	v_add3_u32 v66, v66, v74, s78
	v_lshl_add_u64 v[74:75], s[20:21], 0, v[224:225]
	v_add_f32_e32 v224, 1.0, v226
	v_cmp_gt_f32_e32 vcc, s74, v224
	global_store_short_d16_hi v[74:75], v66, off
	v_max_f32_e64 v66, -v70, 0
	v_cndmask_b32_e64 v225, 0, 32, vcc
	v_ldexp_f32 v224, v224, v225
	v_log_f32_e32 v226, v224
	v_cndmask_b32_e32 v74, 0, v176, vcc
	v_lshl_add_u64 v[224:225], v[130:131], 0, v[96:97]
	v_mul_f32_e32 v70, 0x3f317217, v226
	v_fma_f32 v70, v226, s83, -v70
	v_fmac_f32_e32 v70, 0x3377d1cf, v226
	v_fmac_f32_e32 v70, 0x3f317217, v226
	v_cmp_lt_f32_e64 s[10:11], |v226|, s92
	s_nop 1
	v_cndmask_b32_e64 v70, v226, v70, s[10:11]
	v_sub_f32_e32 v70, v70, v74
	v_add_f32_e32 v66, v66, v70
	v_sub_f32_e32 v66, -0.5, v66
	v_mul_f32_e32 v66, 0x3fb8aa3b, v66
	v_add_f32_e32 v70, v221, v71
	v_exp_f32_e32 v66, v66
	v_mul_f32_e32 v70, 0xbfb8aa3b, v70
	v_exp_f32_e32 v70, v70
	v_xor_b32_e32 v66, 0x80000000, v66
	v_bfe_u32 v71, v66, 16, 1
	v_add_f32_e32 v70, 1.0, v70
	v_add3_u32 v66, v66, v71, s78
	v_rcp_f32_e32 v74, v70
	v_lshlrev_b64 v[70:71], 1, v[224:225]
	v_lshl_add_u64 v[224:225], s[16:17], 0, v[70:71]
	global_store_short_d16_hi v[224:225], v66, off
	v_add_f32_e32 v66, v222, v76
	v_mul_f32_e64 v75, |v66|, s82
	v_exp_f32_e32 v76, v75
	v_bfe_u32 v224, v74, 16, 1
	v_add3_u32 v226, v74, v224, s78
	v_lshl_add_u64 v[224:225], s[18:19], 0, v[70:71]
	v_add_f32_e32 v74, 1.0, v76
	v_cmp_gt_f32_e32 vcc, s74, v74
	global_store_short_d16_hi v[224:225], v226, off
	v_max_f32_e64 v66, -v66, 0
	v_cndmask_b32_e64 v76, 0, 32, vcc
	v_ldexp_f32 v74, v74, v76
	v_log_f32_e32 v76, v74
	global_load_dword v75, v[104:105], off offset:128
	global_load_dword v74, v[104:105], off offset:192
	v_mul_f32_e32 v224, 0x3f317217, v76
	v_fma_f32 v224, v76, s83, -v224
	v_fmac_f32_e32 v224, 0x3377d1cf, v76
	v_fmac_f32_e32 v224, 0x3f317217, v76
	v_cmp_lt_f32_e64 s[10:11], |v76|, s92
	s_nop 1
	v_cndmask_b32_e64 v76, v76, v224, s[10:11]
	v_cndmask_b32_e32 v224, 0, v176, vcc
	v_sub_f32_e32 v76, v76, v224
	v_add_f32_e32 v66, v66, v76
	v_sub_f32_e32 v66, -0.5, v66
	v_mul_f32_e32 v66, 0x3fb8aa3b, v66
	v_exp_f32_e32 v76, v66
	v_bfe_u32 v224, v67, 16, 1
	v_add3_u32 v224, v67, v224, s78
	v_lshl_add_u64 v[66:67], s[20:21], 0, v[70:71]
	global_store_short_d16_hi v[66:67], v224, off
	v_lshl_add_u64 v[66:67], v[136:137], 0, v[96:97]
	v_xor_b32_e32 v70, 0x80000000, v76
	v_bfe_u32 v71, v70, 16, 1
	v_lshlrev_b64 v[66:67], 1, v[66:67]
	v_add3_u32 v76, v70, v71, s78
	v_lshl_add_u64 v[70:71], s[16:17], 0, v[66:67]
	global_store_short_d16_hi v[70:71], v76, off
	v_add_f32_e32 v70, v221, v72
	v_mul_f32_e32 v70, 0xbfb8aa3b, v70
	v_exp_f32_e32 v72, v70
	v_and_b32_e32 v76, 0xffff0000, v223
	global_load_dword v71, v[106:107], off offset:128
	global_load_dword v70, v[106:107], off offset:192
	ds_write_b32 v0, v76 offset:17984
	v_add_f32_e32 v72, 1.0, v72
	v_rcp_f32_e32 v72, v72
	v_and_b32_e32 v76, 0xffff0000, v226
	ds_write_b32 v182, v76 offset:17984
	v_lshl_add_u64 v[224:225], s[18:19], 0, v[66:67]
	v_bfe_u32 v76, v72, 16, 1
	v_add3_u32 v72, v72, v76, s78
	global_store_short_d16_hi v[224:225], v72, off
	v_and_b32_e32 v72, 0xffff0000, v72
	ds_write_b32 v183, v72 offset:17984
	v_bfe_u32 v72, v68, 16, 1
	v_add3_u32 v68, v68, v72, s78
	v_lshl_add_u64 v[66:67], s[20:21], 0, v[66:67]
	global_store_short_d16_hi v[66:67], v68, off
	v_add_f32_e32 v66, v221, v73
	v_mul_f32_e32 v66, 0xbfb8aa3b, v66
	v_exp_f32_e32 v66, v66
	v_add_f32_e32 v76, v222, v77
	v_mul_f32_e64 v77, |v76|, s82
	v_exp_f32_e32 v77, v77
	v_add_f32_e32 v66, 1.0, v66
	v_rcp_f32_e32 v66, v66
	v_max_f32_e64 v67, -v76, 0
	v_add_f32_e32 v72, 1.0, v77
	v_cmp_gt_f32_e32 vcc, s74, v72
	v_bfe_u32 v73, v66, 16, 1
	v_add3_u32 v73, v66, v73, s78
	v_cndmask_b32_e64 v77, 0, 32, vcc
	v_ldexp_f32 v72, v72, v77
	v_and_b32_e32 v66, 0xffff0000, v73
	v_log_f32_e32 v72, v72
	ds_write_b32 v184, v66 offset:17984
	ds_read_b128 v[224:227], v161 offset:13568
	ds_read_b128 v[228:231], v161 offset:13632
	v_mul_f32_e32 v68, 0x3f317217, v72
	v_fma_f32 v68, v72, s83, -v68
	v_fmac_f32_e32 v68, 0x3377d1cf, v72
	v_fmac_f32_e32 v68, 0x3f317217, v72
	v_cmp_lt_f32_e64 s[10:11], |v72|, s92
	s_waitcnt lgkmcnt(1)
	v_mfma_f32_16x16x32_bf16 v[30:33], v[224:227], v[30:33], 0
	v_cndmask_b32_e64 v66, v72, v68, s[10:11]
	v_cndmask_b32_e32 v68, 0, v176, vcc
	v_sub_f32_e32 v66, v66, v68
	v_add_f32_e32 v66, v67, v66
	ds_read_b128 v[224:227], v161 offset:13696
	v_sub_f32_e32 v66, -0.5, v66
	v_mul_f32_e32 v66, 0x3fb8aa3b, v66
	v_exp_f32_e32 v68, v66
	s_waitcnt lgkmcnt(1)
	v_mfma_f32_16x16x32_bf16 v[26:29], v[228:231], v[26:29], v[30:33]
	ds_read_b128 v[228:231], v159 offset:2304
	v_lshl_add_u64 v[66:67], v[134:135], 0, v[96:97]
	v_xor_b32_e32 v68, 0x80000000, v68
	v_bfe_u32 v72, v68, 16, 1
	v_lshlrev_b64 v[66:67], 1, v[66:67]
	ds_read_b128 v[30:33], v161 offset:13760
	v_add3_u32 v68, v68, v72, s78
	s_waitcnt lgkmcnt(2)
	v_mfma_f32_16x16x32_bf16 v[22:25], v[224:227], v[22:25], v[26:29]
	s_nop 2
	v_lshl_add_u64 v[26:27], s[16:17], 0, v[66:67]
	global_store_short_d16_hi v[26:27], v68, off
	ds_read_b128 v[26:29], v159 offset:2368
	s_waitcnt lgkmcnt(2)
	v_mfma_f32_16x16x32_bf16 v[14:17], v[228:231], v[14:17], 0
	s_waitcnt lgkmcnt(0)
	v_mfma_f32_16x16x32_bf16 v[10:13], v[26:29], v[10:13], v[14:17]
	v_mfma_f32_16x16x32_bf16 v[18:21], v[30:33], v[18:21], v[22:25]
	s_nop 6
	v_add_f32_e32 v10, v222, v10
	v_mul_f32_e64 v14, |v10|, s82
	v_exp_f32_e32 v16, v14
	v_lshl_add_u64 v[22:23], s[18:19], 0, v[66:67]
	global_store_short_d16_hi v[22:23], v73, off
	v_bfe_u32 v22, v69, 16, 1
	v_add3_u32 v68, v69, v22, s78
	v_lshl_add_u64 v[14:15], s[20:21], 0, v[66:67]
	ds_read_b128 v[22:25], v159 offset:6912
	ds_read_b128 v[30:33], v159 offset:6976
	global_store_short_d16_hi v[14:15], v68, off
	v_add_f32_e32 v14, 1.0, v16
	v_cmp_gt_f32_e32 vcc, s74, v14
	s_waitcnt lgkmcnt(1)
	v_mfma_f32_16x16x32_bf16 v[6:9], v[22:25], v[6:9], 0
	v_cndmask_b32_e64 v15, 0, 32, vcc
	v_ldexp_f32 v14, v14, v15
	v_log_f32_e32 v14, v14
	s_waitcnt lgkmcnt(0)
	v_mfma_f32_16x16x32_bf16 v[2:5], v[30:33], v[2:5], v[6:9]
	v_cmp_lt_f32_e64 s[10:11], |v14|, s92
	s_nop 1
	v_mul_f32_e32 v9, 0x3f317217, v14
	v_fma_f32 v9, v14, s83, -v9
	v_fmac_f32_e32 v9, 0x3377d1cf, v14
	v_fmac_f32_e32 v9, 0x3f317217, v14
	v_max_f32_e64 v8, -v10, 0
	v_cndmask_b32_e64 v9, v14, v9, s[10:11]
	v_cndmask_b32_e32 v10, 0, v176, vcc
	v_sub_f32_e32 v9, v9, v10
	v_add_f32_e32 v2, v221, v2
	v_add_f32_e32 v8, v8, v9
	v_mul_f32_e32 v2, 0xbfb8aa3b, v2
	v_sub_f32_e32 v8, -0.5, v8
	v_exp_f32_e32 v2, v2
	v_mul_f32_e32 v8, 0x3fb8aa3b, v8
	v_exp_f32_e32 v8, v8
	v_lshl_add_u64 v[6:7], v[128:129], 0, v[96:97]
	v_add_f32_e32 v2, 1.0, v2
	v_rcp_f32_e32 v2, v2
	v_xor_b32_e32 v8, 0x80000000, v8
	v_bfe_u32 v9, v8, 16, 1
	v_lshlrev_b64 v[6:7], 1, v[6:7]
	v_add3_u32 v10, v8, v9, s78
	v_lshl_add_u64 v[8:9], s[16:17], 0, v[6:7]
	global_store_short_d16_hi v[8:9], v10, off
	v_bfe_u32 v8, v2, 16, 1
	v_add3_u32 v2, v2, v8, s78
	v_lshl_add_u64 v[8:9], s[18:19], 0, v[6:7]
	global_store_short_d16_hi v[8:9], v2, off
	v_and_b32_e32 v2, 0xffff0000, v2
	ds_write_b32 v185, v2 offset:17984
	v_add_f32_e32 v2, v222, v11
	v_mul_f32_e64 v8, |v2|, s82
	v_exp_f32_e32 v8, v8
	v_bfe_u32 v9, v18, 16, 1
	v_add3_u32 v9, v18, v9, s78
	v_lshl_add_u64 v[6:7], s[20:21], 0, v[6:7]
	v_add_f32_e32 v8, 1.0, v8
	v_cmp_gt_f32_e32 vcc, s74, v8
	global_store_short_d16_hi v[6:7], v9, off
	v_max_f32_e64 v2, -v2, 0
	v_cndmask_b32_e64 v10, 0, 32, vcc
	v_ldexp_f32 v8, v8, v10
	v_log_f32_e32 v8, v8
	v_add_f32_e32 v3, v221, v3
	v_mul_f32_e32 v3, 0xbfb8aa3b, v3
	v_exp_f32_e32 v3, v3
	v_mul_f32_e32 v9, 0x3f317217, v8
	v_fma_f32 v9, v8, s83, -v9
	v_fmac_f32_e32 v9, 0x3377d1cf, v8
	v_fmac_f32_e32 v9, 0x3f317217, v8
	v_cmp_lt_f32_e64 s[10:11], |v8|, s92
	v_lshl_add_u64 v[6:7], v[142:143], 0, v[96:97]
	v_add_f32_e32 v4, v221, v4
	v_cndmask_b32_e64 v8, v8, v9, s[10:11]
	v_cndmask_b32_e32 v9, 0, v176, vcc
	v_sub_f32_e32 v8, v8, v9
	v_add_f32_e32 v2, v2, v8
	v_sub_f32_e32 v2, -0.5, v2
	v_mul_f32_e32 v2, 0x3fb8aa3b, v2
	v_exp_f32_e32 v2, v2
	v_mul_f32_e32 v4, 0xbfb8aa3b, v4
	v_exp_f32_e32 v4, v4
	v_lshl_add_u64 v[10:11], v[146:147], 0, v[96:97]
	v_xor_b32_e32 v2, 0x80000000, v2
	v_bfe_u32 v8, v2, 16, 1
	v_add3_u32 v8, v2, v8, s78
	v_add_f32_e32 v2, 1.0, v3
	v_rcp_f32_e32 v9, v2
	v_lshlrev_b64 v[2:3], 1, v[6:7]
	v_lshl_add_u64 v[6:7], s[16:17], 0, v[2:3]
	global_store_short_d16_hi v[6:7], v8, off
	v_bfe_u32 v6, v9, 16, 1
	v_add3_u32 v8, v9, v6, s78
	v_lshl_add_u64 v[6:7], s[18:19], 0, v[2:3]
	global_store_short_d16_hi v[6:7], v8, off
	v_and_b32_e32 v6, 0xffff0000, v8
	ds_write_b32 v186, v6 offset:17984
	v_add_f32_e32 v6, v222, v12
	v_mul_f32_e64 v7, |v6|, s82
	v_exp_f32_e32 v7, v7
	v_bfe_u32 v8, v19, 16, 1
	v_add3_u32 v8, v19, v8, s78
	v_lshl_add_u64 v[2:3], s[20:21], 0, v[2:3]
	v_add_f32_e32 v7, 1.0, v7
	v_cmp_gt_f32_e32 vcc, s74, v7
	global_store_short_d16_hi v[2:3], v8, off
	v_max_f32_e64 v6, -v6, 0
	v_cndmask_b32_e64 v9, 0, 32, vcc
	v_ldexp_f32 v7, v7, v9
	v_log_f32_e32 v7, v7
	v_add_f32_e32 v4, 1.0, v4
	v_rcp_f32_e32 v4, v4
	v_lshl_add_u64 v[2:3], v[144:145], 0, v[96:97]
	v_mul_f32_e32 v8, 0x3f317217, v7
	v_fma_f32 v8, v7, s83, -v8
	v_fmac_f32_e32 v8, 0x3377d1cf, v7
	v_fmac_f32_e32 v8, 0x3f317217, v7
	v_cmp_lt_f32_e64 s[10:11], |v7|, s92
	v_lshlrev_b64 v[2:3], 1, v[2:3]
	v_lshlrev_b64 v[22:23], 1, v[10:11]
	v_cndmask_b32_e64 v7, v7, v8, s[10:11]
	v_cndmask_b32_e32 v8, 0, v176, vcc
	v_sub_f32_e32 v7, v7, v8
	v_add_f32_e32 v6, v6, v7
	v_sub_f32_e32 v6, -0.5, v6
	v_mul_f32_e32 v6, 0x3fb8aa3b, v6
	v_exp_f32_e32 v6, v6
	v_lshl_add_u64 v[10:11], s[16:17], 0, v[22:23]
	v_lshl_add_u64 v[14:15], s[18:19], 0, v[22:23]
	v_xor_b32_e32 v6, 0x80000000, v6
	v_bfe_u32 v7, v6, 16, 1
	v_add3_u32 v8, v6, v7, s78
	v_lshl_add_u64 v[6:7], s[16:17], 0, v[2:3]
	global_store_short_d16_hi v[6:7], v8, off
	v_bfe_u32 v6, v4, 16, 1
	v_add3_u32 v4, v4, v6, s78
	v_lshl_add_u64 v[6:7], s[18:19], 0, v[2:3]
	global_store_short_d16_hi v[6:7], v4, off
	v_and_b32_e32 v4, 0xffff0000, v4
	ds_write_b32 v187, v4 offset:17984
	v_add_f32_e32 v4, v222, v13
	v_mul_f32_e64 v6, |v4|, s82
	v_exp_f32_e32 v6, v6
	v_bfe_u32 v7, v20, 16, 1
	v_add3_u32 v7, v20, v7, s78
	v_lshl_add_u64 v[2:3], s[20:21], 0, v[2:3]
	v_add_f32_e32 v6, 1.0, v6
	v_cmp_gt_f32_e32 vcc, s74, v6
	global_store_short_d16_hi v[2:3], v7, off
	v_max_f32_e64 v2, -v4, 0
	v_cndmask_b32_e64 v8, 0, 32, vcc
	v_ldexp_f32 v6, v6, v8
	v_log_f32_e32 v6, v6
	v_add_f32_e32 v4, v221, v5
	v_mul_f32_e32 v4, 0xbfb8aa3b, v4
	v_exp_f32_e32 v4, v4
	v_mul_f32_e32 v3, 0x3f317217, v6
	v_fma_f32 v3, v6, s83, -v3
	v_fmac_f32_e32 v3, 0x3377d1cf, v6
	v_fmac_f32_e32 v3, 0x3f317217, v6
	v_cmp_lt_f32_e64 s[10:11], |v6|, s92
	v_cndmask_b32_e32 v5, 0, v176, vcc
	s_nop 0
	v_cndmask_b32_e64 v3, v6, v3, s[10:11]
	v_sub_f32_e32 v3, v3, v5
	v_add_f32_e32 v2, v2, v3
	v_add_f32_e32 v3, 1.0, v4
	v_rcp_f32_e32 v3, v3
	v_sub_f32_e32 v2, -0.5, v2
	v_mul_f32_e32 v2, 0x3fb8aa3b, v2
	v_exp_f32_e32 v6, v2
	v_bfe_u32 v2, v3, 16, 1
	v_add3_u32 v16, v3, v2, s78
	v_and_b32_e32 v2, 0xffff0000, v16
	ds_write_b32 v188, v2 offset:17984
	ds_read_b128 v[2:5], v161 offset:9216
	v_xor_b32_e32 v6, 0x80000000, v6
	v_bfe_u32 v7, v6, 16, 1
	v_add3_u32 v12, v6, v7, s78
	ds_read_b128 v[6:9], v161 offset:9280
	s_waitcnt vmcnt(25) lgkmcnt(1)
	v_mfma_f32_16x16x32_bf16 v[2:5], v[2:5], v[62:65], 0
	ds_read_b128 v[26:29], v159 offset:64
	global_store_short_d16_hi v[10:11], v12, off
	ds_read_b128 v[10:13], v161 offset:9344
	s_waitcnt lgkmcnt(2)
	v_mfma_f32_16x16x32_bf16 v[2:5], v[6:9], v[58:61], v[2:5]
	v_bfe_u32 v6, v21, 16, 1
	v_add3_u32 v8, v21, v6, s78
	ds_read_b128 v[18:21], v159
	s_waitcnt lgkmcnt(0)
	v_mfma_f32_16x16x32_bf16 v[30:33], v[18:21], v[46:49], 0
	global_store_short_d16_hi v[14:15], v16, off
	ds_read_b128 v[14:17], v161 offset:9408
	v_lshl_add_u64 v[6:7], s[20:21], 0, v[22:23]
	v_mfma_f32_16x16x32_bf16 v[230:233], v[26:29], v[42:45], v[30:33]
	global_store_short_d16_hi v[6:7], v8, off
	v_mfma_f32_16x16x32_bf16 v[2:5], v[10:13], v[54:57], v[2:5]
	s_waitcnt lgkmcnt(0)
	v_mfma_f32_16x16x32_bf16 v[66:69], v[14:17], v[50:53], v[2:5]
	s_waitcnt vmcnt(22)
	s_nop 2
	v_add_f32_e32 v76, v75, v230
	v_mul_f32_e64 v26, |v76|, s82
	v_exp_f32_e32 v72, v26
	global_load_dwordx4 v[14:17], v[120:121], off
	global_load_dwordx4 v[10:13], v[120:121], off offset:64
	global_load_dwordx4 v[6:9], v[122:123], off
	global_load_dwordx4 v[2:5], v[122:123], off offset:64
	global_load_dwordx4 v[22:25], v[124:125], off
	global_load_dwordx4 v[18:21], v[124:125], off offset:64
	ds_read_b128 v[222:225], v159 offset:4608
	ds_read_b128 v[226:229], v159 offset:4672
	v_add_f32_e32 v72, 1.0, v72
	v_cmp_gt_f32_e32 vcc, s74, v72
	s_waitcnt lgkmcnt(1)
	v_mfma_f32_16x16x32_bf16 v[222:225], v[222:225], v[38:41], 0
	v_cndmask_b32_e64 v73, 0, 32, vcc
	v_ldexp_f32 v72, v72, v73
	v_log_f32_e32 v77, v72
	s_waitcnt lgkmcnt(0)
	v_mfma_f32_16x16x32_bf16 v[222:225], v[226:229], v[34:37], v[222:225]
	v_max_f32_e64 v76, -v76, 0
	v_lshl_add_u64 v[72:73], v[132:133], 0, v[110:111]
	v_mul_f32_e32 v221, 0x3f317217, v77
	v_fma_f32 v221, v77, s83, -v221
	v_fmac_f32_e32 v221, 0x3377d1cf, v77
	v_fmac_f32_e32 v221, 0x3f317217, v77
	v_cmp_lt_f32_e64 s[10:11], |v77|, s92
	v_lshlrev_b64 v[72:73], 1, v[72:73]
	global_load_dwordx4 v[30:33], v[124:125], off offset:128
	global_load_dwordx4 v[26:29], v[124:125], off offset:192
	v_cndmask_b32_e64 v77, v77, v221, s[10:11]
	v_cndmask_b32_e32 v221, 0, v176, vcc
	v_sub_f32_e32 v77, v77, v221
	v_add_f32_e32 v76, v76, v77
	v_sub_f32_e32 v76, -0.5, v76
	v_mul_f32_e32 v76, 0x3fb8aa3b, v76
	v_exp_f32_e32 v76, v76
	s_waitcnt vmcnt(26)
	v_add_f32_e32 v77, v71, v222
	v_mul_f32_e32 v77, 0xbfb8aa3b, v77
	v_exp_f32_e32 v77, v77
	v_xor_b32_e32 v76, 0x80000000, v76
	v_bfe_u32 v221, v76, 16, 1
	v_add3_u32 v221, v76, v221, s78
	v_add_f32_e32 v76, 1.0, v77
	v_rcp_f32_e32 v222, v76
	v_lshl_add_u64 v[76:77], s[16:17], 0, v[72:73]
	global_store_short_d16_hi v[76:77], v221, off
	v_bfe_u32 v76, v222, 16, 1
	v_add3_u32 v221, v222, v76, s78
	v_lshl_add_u64 v[76:77], s[18:19], 0, v[72:73]
	global_store_short_d16_hi v[76:77], v221, off
	v_and_b32_e32 v76, 0xffff0000, v221
	ds_write_b32 v0, v76 offset:18048
	v_add_f32_e32 v76, v75, v231
	v_mul_f32_e64 v77, |v76|, s82
	v_exp_f32_e32 v77, v77
	v_bfe_u32 v221, v66, 16, 1
	v_add3_u32 v66, v66, v221, s78
	v_lshl_add_u64 v[72:73], s[20:21], 0, v[72:73]
	v_add_f32_e32 v77, 1.0, v77
	v_cmp_gt_f32_e32 vcc, s74, v77
	global_store_short_d16_hi v[72:73], v66, off
	v_max_f32_e64 v66, -v76, 0
	v_cndmask_b32_e64 v221, 0, 32, vcc
	v_ldexp_f32 v77, v77, v221
	v_log_f32_e32 v77, v77
	v_lshl_add_u64 v[72:73], v[130:131], 0, v[110:111]
	v_lshlrev_b64 v[72:73], 1, v[72:73]
	v_mul_f32_e32 v76, 0x3f317217, v77
	v_fma_f32 v76, v77, s83, -v76
	v_fmac_f32_e32 v76, 0x3377d1cf, v77
	v_fmac_f32_e32 v76, 0x3f317217, v77
	v_cmp_lt_f32_e64 s[10:11], |v77|, s92
	s_nop 1
	v_cndmask_b32_e64 v76, v77, v76, s[10:11]
	v_cndmask_b32_e32 v77, 0, v176, vcc
	v_sub_f32_e32 v76, v76, v77
	v_add_f32_e32 v66, v66, v76
	v_add_f32_e32 v76, v71, v223
	v_mul_f32_e32 v76, 0xbfb8aa3b, v76
	v_sub_f32_e32 v66, -0.5, v66
	v_exp_f32_e32 v76, v76
	v_mul_f32_e32 v66, 0x3fb8aa3b, v66
	v_exp_f32_e32 v66, v66
	v_add_f32_e32 v76, 1.0, v76
	v_rcp_f32_e32 v221, v76
	v_xor_b32_e32 v66, 0x80000000, v66
	v_bfe_u32 v77, v66, 16, 1
	v_add3_u32 v66, v66, v77, s78
	v_lshl_add_u64 v[76:77], s[16:17], 0, v[72:73]
	global_store_short_d16_hi v[76:77], v66, off
	v_bfe_u32 v66, v221, 16, 1
	v_add3_u32 v66, v221, v66, s78
	v_lshl_add_u64 v[76:77], s[18:19], 0, v[72:73]
	global_store_short_d16_hi v[76:77], v66, off
	v_and_b32_e32 v66, 0xffff0000, v66
	v_add_f32_e32 v76, v75, v232
	ds_write_b32 v182, v66 offset:18048
	v_mul_f32_e64 v66, |v76|, s82
	v_exp_f32_e32 v77, v66
	v_bfe_u32 v66, v67, 16, 1
	v_add3_u32 v221, v67, v66, s78
	v_lshl_add_u64 v[66:67], s[20:21], 0, v[72:73]
	v_add_f32_e32 v72, 1.0, v77
	v_cmp_gt_f32_e32 vcc, s74, v72
	global_store_short_d16_hi v[66:67], v221, off
	v_lshl_add_u64 v[66:67], v[136:137], 0, v[110:111]
	v_cndmask_b32_e64 v73, 0, 32, vcc
	v_ldexp_f32 v72, v72, v73
	v_log_f32_e32 v72, v72
	v_max_f32_e64 v73, -v76, 0
	v_lshlrev_b64 v[66:67], 1, v[66:67]
	v_mul_f32_e32 v76, 0x3f317217, v72
	v_fma_f32 v76, v72, s83, -v76
	v_fmac_f32_e32 v76, 0x3377d1cf, v72
	v_fmac_f32_e32 v76, 0x3f317217, v72
	v_cmp_lt_f32_e64 s[10:11], |v72|, s92
	s_nop 1
	v_cndmask_b32_e64 v72, v72, v76, s[10:11]
	v_cndmask_b32_e32 v76, 0, v176, vcc
	v_sub_f32_e32 v72, v72, v76
	v_add_f32_e32 v72, v73, v72
	v_sub_f32_e32 v72, -0.5, v72
	v_mul_f32_e32 v72, 0x3fb8aa3b, v72
	v_exp_f32_e32 v72, v72
	v_add_f32_e32 v73, v71, v224
	v_mul_f32_e32 v73, 0xbfb8aa3b, v73
	v_exp_f32_e32 v73, v73
	v_xor_b32_e32 v72, 0x80000000, v72
	v_bfe_u32 v76, v72, 16, 1
	v_add3_u32 v76, v72, v76, s78
	v_add_f32_e32 v72, 1.0, v73
	v_rcp_f32_e32 v77, v72
	v_lshl_add_u64 v[72:73], s[16:17], 0, v[66:67]
	global_store_short_d16_hi v[72:73], v76, off
	v_bfe_u32 v72, v77, 16, 1
	v_add3_u32 v76, v77, v72, s78
	v_lshl_add_u64 v[72:73], s[18:19], 0, v[66:67]
	global_store_short_d16_hi v[72:73], v76, off
	v_and_b32_e32 v72, 0xffff0000, v76
	ds_write_b32 v183, v72 offset:18048
	v_bfe_u32 v72, v68, 16, 1
	v_add3_u32 v68, v68, v72, s78
	v_lshl_add_u64 v[66:67], s[20:21], 0, v[66:67]
	global_store_short_d16_hi v[66:67], v68, off
	v_add_f32_e32 v66, v71, v225
	v_mul_f32_e32 v66, 0xbfb8aa3b, v66
	v_exp_f32_e32 v66, v66
	v_add_f32_e32 v73, v75, v233
	v_mul_f32_e64 v76, |v73|, s82
	v_exp_f32_e32 v76, v76
	v_add_f32_e32 v66, 1.0, v66
	v_rcp_f32_e32 v66, v66
	v_max_f32_e64 v67, -v73, 0
	v_add_f32_e32 v72, 1.0, v76
	v_cmp_gt_f32_e32 vcc, s74, v72
	v_bfe_u32 v73, v66, 16, 1
	v_add3_u32 v73, v66, v73, s78
	v_cndmask_b32_e64 v76, 0, 32, vcc
	v_ldexp_f32 v72, v72, v76
	v_and_b32_e32 v66, 0xffff0000, v73
	v_log_f32_e32 v72, v72
	ds_write_b32 v184, v66 offset:18048
	ds_read_b128 v[222:225], v161 offset:13568
	ds_read_b128 v[226:229], v161 offset:13632
	v_mul_f32_e32 v68, 0x3f317217, v72
	v_fma_f32 v68, v72, s83, -v68
	v_fmac_f32_e32 v68, 0x3377d1cf, v72
	v_fmac_f32_e32 v68, 0x3f317217, v72
	v_cmp_lt_f32_e64 s[10:11], |v72|, s92
	s_waitcnt lgkmcnt(1)
	v_mfma_f32_16x16x32_bf16 v[62:65], v[222:225], v[62:65], 0
	v_cndmask_b32_e64 v66, v72, v68, s[10:11]
	v_cndmask_b32_e32 v68, 0, v176, vcc
	v_sub_f32_e32 v66, v66, v68
	v_add_f32_e32 v66, v67, v66
	ds_read_b128 v[222:225], v161 offset:13696
	v_sub_f32_e32 v66, -0.5, v66
	v_mul_f32_e32 v66, 0x3fb8aa3b, v66
	v_exp_f32_e32 v68, v66
	s_waitcnt lgkmcnt(1)
	v_mfma_f32_16x16x32_bf16 v[58:61], v[226:229], v[58:61], v[62:65]
	ds_read_b128 v[226:229], v159 offset:2304
	v_lshl_add_u64 v[66:67], v[134:135], 0, v[110:111]
	v_xor_b32_e32 v68, 0x80000000, v68
	v_bfe_u32 v72, v68, 16, 1
	v_lshlrev_b64 v[66:67], 1, v[66:67]
	ds_read_b128 v[62:65], v161 offset:13760
	v_add3_u32 v68, v68, v72, s78
	s_waitcnt lgkmcnt(2)
	v_mfma_f32_16x16x32_bf16 v[54:57], v[222:225], v[54:57], v[58:61]
	s_nop 2
	v_lshl_add_u64 v[58:59], s[16:17], 0, v[66:67]
	global_store_short_d16_hi v[58:59], v68, off
	ds_read_b128 v[58:61], v159 offset:2368
	s_waitcnt lgkmcnt(2)
	v_mfma_f32_16x16x32_bf16 v[46:49], v[226:229], v[46:49], 0
	s_waitcnt lgkmcnt(0)
	v_mfma_f32_16x16x32_bf16 v[42:45], v[58:61], v[42:45], v[46:49]
	v_mfma_f32_16x16x32_bf16 v[50:53], v[62:65], v[50:53], v[54:57]
	s_nop 6
	v_add_f32_e32 v42, v75, v42
	v_mul_f32_e64 v46, |v42|, s82
	v_exp_f32_e32 v48, v46
	v_lshl_add_u64 v[54:55], s[18:19], 0, v[66:67]
	global_store_short_d16_hi v[54:55], v73, off
	v_bfe_u32 v54, v69, 16, 1
	v_add3_u32 v68, v69, v54, s78
	v_lshl_add_u64 v[46:47], s[20:21], 0, v[66:67]
	ds_read_b128 v[54:57], v159 offset:6912
	ds_read_b128 v[62:65], v159 offset:6976
	global_store_short_d16_hi v[46:47], v68, off
	v_add_f32_e32 v46, 1.0, v48
	v_cmp_gt_f32_e32 vcc, s74, v46
	s_waitcnt lgkmcnt(1)
	v_mfma_f32_16x16x32_bf16 v[38:41], v[54:57], v[38:41], 0
	v_cndmask_b32_e64 v47, 0, 32, vcc
	v_ldexp_f32 v46, v46, v47
	v_log_f32_e32 v46, v46
	s_waitcnt lgkmcnt(0)
	v_mfma_f32_16x16x32_bf16 v[34:37], v[62:65], v[34:37], v[38:41]
	v_cmp_lt_f32_e64 s[10:11], |v46|, s92
	s_nop 1
	v_mul_f32_e32 v41, 0x3f317217, v46
	v_fma_f32 v41, v46, s83, -v41
	v_fmac_f32_e32 v41, 0x3377d1cf, v46
	v_fmac_f32_e32 v41, 0x3f317217, v46
	v_max_f32_e64 v40, -v42, 0
	v_cndmask_b32_e64 v41, v46, v41, s[10:11]
	v_cndmask_b32_e32 v42, 0, v176, vcc
	v_sub_f32_e32 v41, v41, v42
	v_add_f32_e32 v34, v71, v34
	v_add_f32_e32 v40, v40, v41
	v_mul_f32_e32 v34, 0xbfb8aa3b, v34
	v_sub_f32_e32 v40, -0.5, v40
	v_exp_f32_e32 v34, v34
	v_mul_f32_e32 v40, 0x3fb8aa3b, v40
	v_exp_f32_e32 v40, v40
	v_lshl_add_u64 v[38:39], v[128:129], 0, v[110:111]
	v_add_f32_e32 v34, 1.0, v34
	v_rcp_f32_e32 v34, v34
	v_xor_b32_e32 v40, 0x80000000, v40
	v_bfe_u32 v41, v40, 16, 1
	v_lshlrev_b64 v[38:39], 1, v[38:39]
	v_add3_u32 v42, v40, v41, s78
	v_lshl_add_u64 v[40:41], s[16:17], 0, v[38:39]
	global_store_short_d16_hi v[40:41], v42, off
	v_bfe_u32 v40, v34, 16, 1
	v_add3_u32 v34, v34, v40, s78
	v_lshl_add_u64 v[40:41], s[18:19], 0, v[38:39]
	global_store_short_d16_hi v[40:41], v34, off
	v_and_b32_e32 v34, 0xffff0000, v34
	ds_write_b32 v185, v34 offset:18048
	v_add_f32_e32 v34, v75, v43
	v_mul_f32_e64 v40, |v34|, s82
	v_exp_f32_e32 v40, v40
	v_bfe_u32 v41, v50, 16, 1
	v_add3_u32 v41, v50, v41, s78
	v_lshl_add_u64 v[38:39], s[20:21], 0, v[38:39]
	v_add_f32_e32 v40, 1.0, v40
	v_cmp_gt_f32_e32 vcc, s74, v40
	global_store_short_d16_hi v[38:39], v41, off
	v_max_f32_e64 v34, -v34, 0
	v_cndmask_b32_e64 v42, 0, 32, vcc
	v_ldexp_f32 v40, v40, v42
	v_log_f32_e32 v40, v40
	v_add_f32_e32 v35, v71, v35
	v_mul_f32_e32 v35, 0xbfb8aa3b, v35
	v_exp_f32_e32 v35, v35
	v_mul_f32_e32 v41, 0x3f317217, v40
	v_fma_f32 v41, v40, s83, -v41
	v_fmac_f32_e32 v41, 0x3377d1cf, v40
	v_fmac_f32_e32 v41, 0x3f317217, v40
	v_cmp_lt_f32_e64 s[10:11], |v40|, s92
	v_lshl_add_u64 v[38:39], v[142:143], 0, v[110:111]
	v_add_f32_e32 v36, v71, v36
	v_cndmask_b32_e64 v40, v40, v41, s[10:11]
	v_cndmask_b32_e32 v41, 0, v176, vcc
	v_sub_f32_e32 v40, v40, v41
	v_add_f32_e32 v34, v34, v40
	v_sub_f32_e32 v34, -0.5, v34
	v_mul_f32_e32 v34, 0x3fb8aa3b, v34
	v_exp_f32_e32 v34, v34
	v_mul_f32_e32 v36, 0xbfb8aa3b, v36
	v_exp_f32_e32 v36, v36
	v_xor_b32_e32 v34, 0x80000000, v34
	v_bfe_u32 v40, v34, 16, 1
	v_add3_u32 v40, v34, v40, s78
	v_add_f32_e32 v34, 1.0, v35
	v_rcp_f32_e32 v41, v34
	v_lshlrev_b64 v[34:35], 1, v[38:39]
	v_lshl_add_u64 v[38:39], s[16:17], 0, v[34:35]
	global_store_short_d16_hi v[38:39], v40, off
	v_bfe_u32 v38, v41, 16, 1
	v_add3_u32 v40, v41, v38, s78
	v_lshl_add_u64 v[38:39], s[18:19], 0, v[34:35]
	global_store_short_d16_hi v[38:39], v40, off
	v_and_b32_e32 v38, 0xffff0000, v40
	ds_write_b32 v186, v38 offset:18048
	v_add_f32_e32 v38, v75, v44
	v_mul_f32_e64 v39, |v38|, s82
	v_exp_f32_e32 v39, v39
	v_bfe_u32 v40, v51, 16, 1
	v_add3_u32 v40, v51, v40, s78
	v_lshl_add_u64 v[34:35], s[20:21], 0, v[34:35]
	v_add_f32_e32 v39, 1.0, v39
	v_cmp_gt_f32_e32 vcc, s74, v39
	global_store_short_d16_hi v[34:35], v40, off
	v_max_f32_e64 v38, -v38, 0
	v_cndmask_b32_e64 v41, 0, 32, vcc
	v_ldexp_f32 v39, v39, v41
	v_log_f32_e32 v39, v39
	v_add_f32_e32 v36, 1.0, v36
	v_rcp_f32_e32 v36, v36
	v_lshl_add_u64 v[34:35], v[144:145], 0, v[110:111]
	v_mul_f32_e32 v40, 0x3f317217, v39
	v_fma_f32 v40, v39, s83, -v40
	v_fmac_f32_e32 v40, 0x3377d1cf, v39
	v_fmac_f32_e32 v40, 0x3f317217, v39
	v_cmp_lt_f32_e64 s[10:11], |v39|, s92
	v_lshlrev_b64 v[34:35], 1, v[34:35]
	v_lshl_add_u64 v[50:51], v[146:147], 0, v[110:111]
	v_cndmask_b32_e64 v39, v39, v40, s[10:11]
	v_cndmask_b32_e32 v40, 0, v176, vcc
	v_sub_f32_e32 v39, v39, v40
	v_add_f32_e32 v38, v38, v39
	v_sub_f32_e32 v38, -0.5, v38
	v_mul_f32_e32 v38, 0x3fb8aa3b, v38
	v_exp_f32_e32 v38, v38
	s_nop 0
	v_xor_b32_e32 v38, 0x80000000, v38
	v_bfe_u32 v39, v38, 16, 1
	v_add3_u32 v40, v38, v39, s78
	v_lshl_add_u64 v[38:39], s[16:17], 0, v[34:35]
	global_store_short_d16_hi v[38:39], v40, off
	v_bfe_u32 v38, v36, 16, 1
	v_add3_u32 v36, v36, v38, s78
	v_lshl_add_u64 v[38:39], s[18:19], 0, v[34:35]
	global_store_short_d16_hi v[38:39], v36, off
	v_add_f32_e32 v38, v75, v45
	v_mul_f32_e64 v39, |v38|, s82
	v_exp_f32_e32 v39, v39
	v_and_b32_e32 v36, 0xffff0000, v36
	ds_write_b32 v187, v36 offset:18048
	v_bfe_u32 v36, v52, 16, 1
	v_add3_u32 v36, v52, v36, s78
	v_add_f32_e32 v39, 1.0, v39
	v_lshl_add_u64 v[34:35], s[20:21], 0, v[34:35]
	v_cmp_gt_f32_e32 vcc, s74, v39
	global_store_short_d16_hi v[34:35], v36, off
	v_add_f32_e32 v35, v71, v37
	v_cndmask_b32_e64 v40, 0, 32, vcc
	v_mul_f32_e32 v35, 0xbfb8aa3b, v35
	v_ldexp_f32 v39, v39, v40
	v_exp_f32_e32 v35, v35
	v_log_f32_e32 v39, v39
	v_cndmask_b32_e32 v40, 0, v176, vcc
	v_max_f32_e64 v38, -v38, 0
	v_add_f32_e32 v35, 1.0, v35
	v_mul_f32_e32 v34, 0x3f317217, v39
	v_rcp_f32_e32 v35, v35
	v_fma_f32 v34, v39, s83, -v34
	v_fmac_f32_e32 v34, 0x3377d1cf, v39
	v_fmac_f32_e32 v34, 0x3f317217, v39
	v_cmp_lt_f32_e64 s[10:11], |v39|, s92
	s_nop 1
	v_cndmask_b32_e64 v39, v39, v34, s[10:11]
	v_bfe_u32 v34, v35, 16, 1
	v_add3_u32 v52, v35, v34, s78
	v_and_b32_e32 v34, 0xffff0000, v52
	ds_write_b32 v188, v34 offset:18048
	ds_read_b128 v[34:37], v161 offset:9216
	v_sub_f32_e32 v39, v39, v40
	v_add_f32_e32 v38, v38, v39
	v_sub_f32_e32 v42, -0.5, v38
	ds_read_b128 v[38:41], v161 offset:9280
	v_mul_f32_e32 v42, 0x3fb8aa3b, v42
	v_exp_f32_e32 v46, v42
	ds_read_b128 v[42:45], v161 offset:9344
	s_waitcnt vmcnt(24) lgkmcnt(2)
	v_mfma_f32_16x16x32_bf16 v[34:37], v[34:37], v[22:25], 0
	v_xor_b32_e32 v54, 0x80000000, v46
	v_bfe_u32 v55, v54, 16, 1
	v_add3_u32 v56, v54, v55, s78
	s_waitcnt vmcnt(23) lgkmcnt(1)
	v_mfma_f32_16x16x32_bf16 v[34:37], v[38:41], v[18:21], v[34:37]
	ds_read_b128 v[38:41], v159
	v_lshlrev_b64 v[54:55], 1, v[50:51]
	ds_read_b128 v[46:49], v161 offset:9408
	s_waitcnt vmcnt(22) lgkmcnt(2)
	v_mfma_f32_16x16x32_bf16 v[34:37], v[42:45], v[30:33], v[34:37]
	v_lshl_add_u64 v[42:43], s[16:17], 0, v[54:55]
	global_store_short_d16_hi v[42:43], v56, off
	ds_read_b128 v[42:45], v159 offset:64
	s_waitcnt lgkmcnt(2)
	v_mfma_f32_16x16x32_bf16 v[38:41], v[38:41], v[14:17], 0
	s_waitcnt lgkmcnt(0)
	v_mfma_f32_16x16x32_bf16 v[38:41], v[42:45], v[10:13], v[38:41]
	s_waitcnt vmcnt(22)
	v_mfma_f32_16x16x32_bf16 v[34:37], v[46:49], v[26:29], v[34:37]
	v_lshl_add_u64 v[46:47], s[18:19], 0, v[54:55]
	s_nop 4
	v_add_f32_e32 v38, v74, v38
	global_store_short_d16_hi v[46:47], v52, off
	v_bfe_u32 v46, v53, 16, 1
	v_mul_f32_e64 v42, |v38|, s82
	v_add3_u32 v56, v53, v46, s78
	ds_read_b128 v[46:49], v159 offset:4608
	ds_read_b128 v[50:53], v159 offset:4672
	v_exp_f32_e32 v57, v42
	v_lshl_add_u64 v[42:43], s[20:21], 0, v[54:55]
	global_store_short_d16_hi v[42:43], v56, off
	s_waitcnt lgkmcnt(1)
	v_mfma_f32_16x16x32_bf16 v[42:45], v[46:49], v[6:9], 0
	v_add_f32_e32 v46, 1.0, v57
	v_cmp_gt_f32_e32 vcc, s74, v46
	v_max_f32_e64 v38, -v38, 0
	s_waitcnt lgkmcnt(0)
	v_mfma_f32_16x16x32_bf16 v[42:45], v[50:53], v[2:5], v[42:45]
	v_cndmask_b32_e64 v47, 0, 32, vcc
	v_ldexp_f32 v46, v46, v47
	v_log_f32_e32 v48, v46
	v_lshl_add_u64 v[46:47], v[132:133], 0, v[118:119]
	v_lshlrev_b64 v[46:47], 1, v[46:47]
	s_nop 2
	v_add_f32_e32 v42, v70, v42
	v_mul_f32_e32 v49, 0x3f317217, v48
	v_fma_f32 v49, v48, s83, -v49
	v_fmac_f32_e32 v49, 0x3377d1cf, v48
	v_fmac_f32_e32 v49, 0x3f317217, v48
	v_cmp_lt_f32_e64 s[10:11], |v48|, s92
	v_mul_f32_e32 v42, 0xbfb8aa3b, v42
	v_exp_f32_e32 v42, v42
	v_cndmask_b32_e64 v48, v48, v49, s[10:11]
	v_cndmask_b32_e32 v49, 0, v176, vcc
	v_sub_f32_e32 v48, v48, v49
	v_add_f32_e32 v38, v38, v48
	v_sub_f32_e32 v38, -0.5, v38
	v_mul_f32_e32 v38, 0x3fb8aa3b, v38
	v_exp_f32_e32 v38, v38
	v_add_f32_e32 v42, 1.0, v42
	v_rcp_f32_e32 v42, v42
	v_xor_b32_e32 v38, 0x80000000, v38
	v_bfe_u32 v48, v38, 16, 1
	v_add3_u32 v38, v38, v48, s78
	v_lshl_add_u64 v[48:49], s[16:17], 0, v[46:47]
	global_store_short_d16_hi v[48:49], v38, off
	v_bfe_u32 v38, v42, 16, 1
	v_add3_u32 v38, v42, v38, s78
	v_lshl_add_u64 v[48:49], s[18:19], 0, v[46:47]
	global_store_short_d16_hi v[48:49], v38, off
	v_and_b32_e32 v38, 0xffff0000, v38
	ds_write_b32 v0, v38 offset:18112
	v_add_f32_e32 v0, v74, v39
	v_mul_f32_e64 v38, |v0|, s82
	v_exp_f32_e32 v42, v38
	v_bfe_u32 v38, v34, 16, 1
	v_add3_u32 v34, v34, v38, s78
	v_lshl_add_u64 v[38:39], s[20:21], 0, v[46:47]
	v_add_f32_e32 v42, 1.0, v42
	v_cmp_gt_f32_e32 vcc, s74, v42
	global_store_short_d16_hi v[38:39], v34, off
	v_max_f32_e64 v0, -v0, 0
	v_cndmask_b32_e64 v46, 0, 32, vcc
	v_ldexp_f32 v42, v42, v46
	v_log_f32_e32 v42, v42
	v_lshl_add_u64 v[38:39], v[130:131], 0, v[118:119]
	v_lshlrev_b64 v[38:39], 1, v[38:39]
	v_mul_f32_e32 v34, 0x3f317217, v42
	v_fma_f32 v34, v42, s83, -v34
	v_fmac_f32_e32 v34, 0x3377d1cf, v42
	v_fmac_f32_e32 v34, 0x3f317217, v42
	v_cmp_lt_f32_e64 s[10:11], |v42|, s92
	s_nop 1
	v_cndmask_b32_e64 v34, v42, v34, s[10:11]
	v_cndmask_b32_e32 v42, 0, v176, vcc
	v_sub_f32_e32 v34, v34, v42
	v_add_f32_e32 v0, v0, v34
	v_add_f32_e32 v34, v70, v43
	v_mul_f32_e32 v34, 0xbfb8aa3b, v34
	v_sub_f32_e32 v0, -0.5, v0
	v_exp_f32_e32 v34, v34
	v_mul_f32_e32 v0, 0x3fb8aa3b, v0
	v_exp_f32_e32 v0, v0
	v_add_f32_e32 v34, 1.0, v34
	v_rcp_f32_e32 v34, v34
	v_xor_b32_e32 v0, 0x80000000, v0
	v_bfe_u32 v42, v0, 16, 1
	v_add3_u32 v0, v0, v42, s78
	v_lshl_add_u64 v[42:43], s[16:17], 0, v[38:39]
	global_store_short_d16_hi v[42:43], v0, off
	v_bfe_u32 v0, v34, 16, 1
	v_add3_u32 v0, v34, v0, s78
	v_lshl_add_u64 v[42:43], s[18:19], 0, v[38:39]
	global_store_short_d16_hi v[42:43], v0, off
	v_and_b32_e32 v0, 0xffff0000, v0
	ds_write_b32 v182, v0 offset:18112
	v_add_f32_e32 v0, v74, v40
	v_mul_f32_e64 v34, |v0|, s82
	v_exp_f32_e32 v40, v34
	v_bfe_u32 v34, v35, 16, 1
	v_add3_u32 v42, v35, v34, s78
	v_lshl_add_u64 v[34:35], s[20:21], 0, v[38:39]
	v_add_f32_e32 v38, 1.0, v40
	v_cmp_gt_f32_e32 vcc, s74, v38
	v_max_f32_e64 v0, -v0, 0
	global_store_short_d16_hi v[34:35], v42, off
	v_cndmask_b32_e64 v39, 0, 32, vcc
	v_ldexp_f32 v38, v38, v39
	v_log_f32_e32 v38, v38
	v_lshl_add_u64 v[34:35], v[136:137], 0, v[118:119]
	v_lshlrev_b64 v[34:35], 1, v[34:35]
	v_mul_f32_e32 v39, 0x3f317217, v38
	v_fma_f32 v39, v38, s83, -v39
	v_fmac_f32_e32 v39, 0x3377d1cf, v38
	v_fmac_f32_e32 v39, 0x3f317217, v38
	v_cmp_lt_f32_e64 s[10:11], |v38|, s92
	s_nop 1
	v_cndmask_b32_e64 v38, v38, v39, s[10:11]
	v_cndmask_b32_e32 v39, 0, v176, vcc
	v_sub_f32_e32 v38, v38, v39
	v_add_f32_e32 v0, v0, v38
	v_add_f32_e32 v38, v70, v44
	v_mul_f32_e32 v38, 0xbfb8aa3b, v38
	v_sub_f32_e32 v0, -0.5, v0
	v_exp_f32_e32 v38, v38
	v_mul_f32_e32 v0, 0x3fb8aa3b, v0
	v_exp_f32_e32 v0, v0
	v_add_f32_e32 v38, 1.0, v38
	v_rcp_f32_e32 v40, v38
	v_xor_b32_e32 v0, 0x80000000, v0
	v_bfe_u32 v39, v0, 16, 1
	v_add3_u32 v0, v0, v39, s78
	v_lshl_add_u64 v[38:39], s[16:17], 0, v[34:35]
	global_store_short_d16_hi v[38:39], v0, off
	v_bfe_u32 v0, v40, 16, 1
	v_add3_u32 v0, v40, v0, s78
	v_lshl_add_u64 v[38:39], s[18:19], 0, v[34:35]
	global_store_short_d16_hi v[38:39], v0, off
	v_and_b32_e32 v0, 0xffff0000, v0
	ds_write_b32 v183, v0 offset:18112
	v_bfe_u32 v0, v36, 16, 1
	v_add3_u32 v0, v36, v0, s78
	v_lshl_add_u64 v[34:35], s[20:21], 0, v[34:35]
	global_store_short_d16_hi v[34:35], v0, off
	v_add_f32_e32 v35, v70, v45
	v_mul_f32_e32 v35, 0xbfb8aa3b, v35
	v_exp_f32_e32 v35, v35
	v_add_f32_e32 v38, v74, v41
	v_mul_f32_e64 v39, |v38|, s82
	v_exp_f32_e32 v39, v39
	v_add_f32_e32 v35, 1.0, v35
	v_rcp_f32_e32 v35, v35
	v_max_f32_e64 v0, -v38, 0
	v_add_f32_e32 v36, 1.0, v39
	v_cmp_gt_f32_e32 vcc, s74, v36
	v_bfe_u32 v38, v35, 16, 1
	v_add3_u32 v50, v35, v38, s78
	v_cndmask_b32_e64 v39, 0, 32, vcc
	v_ldexp_f32 v36, v36, v39
	v_log_f32_e32 v36, v36
	v_and_b32_e32 v35, 0xffff0000, v50
	ds_write_b32 v184, v35 offset:18112
	ds_read_b128 v[38:41], v161 offset:13568
	ds_read_b128 v[42:45], v161 offset:13632
	v_mul_f32_e32 v34, 0x3f317217, v36
	v_fma_f32 v34, v36, s83, -v34
	v_fmac_f32_e32 v34, 0x3377d1cf, v36
	v_fmac_f32_e32 v34, 0x3f317217, v36
	v_cmp_lt_f32_e64 s[10:11], |v36|, s92
	ds_read_b128 v[46:49], v161 offset:13696
	s_waitcnt lgkmcnt(2)
	v_mfma_f32_16x16x32_bf16 v[22:25], v[38:41], v[22:25], 0
	v_cndmask_b32_e64 v34, v36, v34, s[10:11]
	v_cndmask_b32_e32 v36, 0, v176, vcc
	v_sub_f32_e32 v34, v34, v36
	v_add_f32_e32 v0, v0, v34
	v_sub_f32_e32 v0, -0.5, v0
	v_mul_f32_e32 v0, 0x3fb8aa3b, v0
	v_exp_f32_e32 v0, v0
	s_waitcnt lgkmcnt(1)
	v_mfma_f32_16x16x32_bf16 v[18:21], v[42:45], v[18:21], v[22:25]
	v_lshl_add_u64 v[34:35], v[134:135], 0, v[118:119]
	v_lshlrev_b64 v[34:35], 1, v[34:35]
	v_xor_b32_e32 v0, 0x80000000, v0
	ds_read_b128 v[22:25], v159 offset:2304
	v_bfe_u32 v36, v0, 16, 1
	ds_read_b128 v[38:41], v161 offset:13760
	v_add3_u32 v0, v0, v36, s78
	s_waitcnt lgkmcnt(2)
	v_mfma_f32_16x16x32_bf16 v[18:21], v[46:49], v[30:33], v[18:21]
	v_lshl_add_u64 v[30:31], s[16:17], 0, v[34:35]
	global_store_short_d16_hi v[30:31], v0, off
	ds_read_b128 v[30:33], v159 offset:2368
	s_waitcnt lgkmcnt(2)
	v_mfma_f32_16x16x32_bf16 v[14:17], v[22:25], v[14:17], 0
	v_bfe_u32 v0, v37, 16, 1
	v_add3_u32 v0, v37, v0, s78
	s_waitcnt lgkmcnt(0)
	v_mfma_f32_16x16x32_bf16 v[10:13], v[30:33], v[10:13], v[14:17]
	v_mfma_f32_16x16x32_bf16 v[18:21], v[38:41], v[26:29], v[18:21]
	s_nop 6
	v_add_f32_e32 v10, v74, v10
	v_mul_f32_e64 v14, |v10|, s82
	v_exp_f32_e32 v16, v14
	v_lshl_add_u64 v[26:27], s[18:19], 0, v[34:35]
	global_store_short_d16_hi v[26:27], v50, off
	v_lshl_add_u64 v[14:15], s[20:21], 0, v[34:35]
	ds_read_b128 v[22:25], v159 offset:6912
	ds_read_b128 v[26:29], v159 offset:6976
	global_store_short_d16_hi v[14:15], v0, off
	v_add_f32_e32 v0, 1.0, v16
	v_cmp_gt_f32_e32 vcc, s74, v0
	s_waitcnt lgkmcnt(1)
	v_mfma_f32_16x16x32_bf16 v[6:9], v[22:25], v[6:9], 0
	v_cndmask_b32_e64 v14, 0, 32, vcc
	v_ldexp_f32 v0, v0, v14
	v_log_f32_e32 v0, v0
	s_waitcnt lgkmcnt(0)
	v_mfma_f32_16x16x32_bf16 v[2:5], v[26:29], v[2:5], v[6:9]
	v_cmp_lt_f32_e64 s[10:11], |v0|, s92
	s_nop 1
	v_mul_f32_e32 v9, 0x3f317217, v0
	v_fma_f32 v9, v0, s83, -v9
	v_fmac_f32_e32 v9, 0x3377d1cf, v0
	v_fmac_f32_e32 v9, 0x3f317217, v0
	v_cndmask_b32_e64 v0, v0, v9, s[10:11]
	v_cndmask_b32_e32 v9, 0, v176, vcc
	v_max_f32_e64 v8, -v10, 0
	v_sub_f32_e32 v0, v0, v9
	v_add_f32_e32 v2, v70, v2
	v_add_f32_e32 v0, v8, v0
	v_mul_f32_e32 v2, 0xbfb8aa3b, v2
	v_sub_f32_e32 v0, -0.5, v0
	v_exp_f32_e32 v2, v2
	v_mul_f32_e32 v0, 0x3fb8aa3b, v0
	v_exp_f32_e32 v0, v0
	v_lshl_add_u64 v[6:7], v[128:129], 0, v[118:119]
	v_add_f32_e32 v2, 1.0, v2
	v_rcp_f32_e32 v2, v2
	v_xor_b32_e32 v0, 0x80000000, v0
	v_bfe_u32 v8, v0, 16, 1
	v_lshlrev_b64 v[6:7], 1, v[6:7]
	v_add3_u32 v0, v0, v8, s78
	v_lshl_add_u64 v[8:9], s[16:17], 0, v[6:7]
	global_store_short_d16_hi v[8:9], v0, off
	v_bfe_u32 v0, v2, 16, 1
	v_add3_u32 v0, v2, v0, s78
	v_lshl_add_u64 v[8:9], s[18:19], 0, v[6:7]
	global_store_short_d16_hi v[8:9], v0, off
	v_and_b32_e32 v0, 0xffff0000, v0
	ds_write_b32 v185, v0 offset:18112
	v_add_f32_e32 v0, v74, v11
	v_mul_f32_e64 v2, |v0|, s82
	v_exp_f32_e32 v2, v2
	v_bfe_u32 v8, v18, 16, 1
	v_add3_u32 v8, v18, v8, s78
	v_lshl_add_u64 v[6:7], s[20:21], 0, v[6:7]
	v_add_f32_e32 v2, 1.0, v2
	v_cmp_gt_f32_e32 vcc, s74, v2
	global_store_short_d16_hi v[6:7], v8, off
	v_max_f32_e64 v0, -v0, 0
	v_cndmask_b32_e64 v9, 0, 32, vcc
	v_ldexp_f32 v2, v2, v9
	v_log_f32_e32 v2, v2
	v_lshl_add_u64 v[6:7], v[142:143], 0, v[118:119]
	v_add_f32_e32 v4, v70, v4
	v_mul_f32_e32 v4, 0xbfb8aa3b, v4
	v_mul_f32_e32 v8, 0x3f317217, v2
	v_fma_f32 v8, v2, s83, -v8
	v_fmac_f32_e32 v8, 0x3377d1cf, v2
	v_fmac_f32_e32 v8, 0x3f317217, v2
	v_cmp_lt_f32_e64 s[10:11], |v2|, s92
	v_exp_f32_e32 v4, v4
	s_nop 0
	v_cndmask_b32_e64 v2, v2, v8, s[10:11]
	v_cndmask_b32_e32 v8, 0, v176, vcc
	v_sub_f32_e32 v2, v2, v8
	v_add_f32_e32 v0, v0, v2
	v_add_f32_e32 v2, v70, v3
	v_sub_f32_e32 v0, -0.5, v0
	v_mul_f32_e32 v2, 0xbfb8aa3b, v2
	v_mul_f32_e32 v0, 0x3fb8aa3b, v0
	v_exp_f32_e32 v2, v2
	v_exp_f32_e32 v0, v0
	v_add_f32_e32 v4, 1.0, v4
	v_rcp_f32_e32 v4, v4
	v_add_f32_e32 v2, 1.0, v2
	v_xor_b32_e32 v0, 0x80000000, v0
	v_rcp_f32_e32 v8, v2
	v_bfe_u32 v3, v0, 16, 1
	v_add3_u32 v0, v0, v3, s78
	v_lshlrev_b64 v[2:3], 1, v[6:7]
	v_lshl_add_u64 v[6:7], s[16:17], 0, v[2:3]
	global_store_short_d16_hi v[6:7], v0, off
	v_bfe_u32 v0, v8, 16, 1
	v_add3_u32 v0, v8, v0, s78
	v_lshl_add_u64 v[6:7], s[18:19], 0, v[2:3]
	global_store_short_d16_hi v[6:7], v0, off
	v_and_b32_e32 v0, 0xffff0000, v0
	ds_write_b32 v186, v0 offset:18112
	v_add_f32_e32 v0, v74, v12
	v_mul_f32_e64 v6, |v0|, s82
	v_exp_f32_e32 v6, v6
	v_bfe_u32 v7, v19, 16, 1
	v_add3_u32 v7, v19, v7, s78
	v_lshl_add_u64 v[2:3], s[20:21], 0, v[2:3]
	v_add_f32_e32 v6, 1.0, v6
	v_cmp_gt_f32_e32 vcc, s74, v6
	global_store_short_d16_hi v[2:3], v7, off
	v_max_f32_e64 v0, -v0, 0
	v_cndmask_b32_e64 v8, 0, 32, vcc
	v_ldexp_f32 v6, v6, v8
	v_log_f32_e32 v6, v6
	v_lshl_add_u64 v[2:3], v[144:145], 0, v[118:119]
	v_lshlrev_b64 v[2:3], 1, v[2:3]
	v_mul_f32_e32 v7, 0x3f317217, v6
	v_fma_f32 v7, v6, s83, -v7
	v_fmac_f32_e32 v7, 0x3377d1cf, v6
	v_fmac_f32_e32 v7, 0x3f317217, v6
	v_cmp_lt_f32_e64 s[10:11], |v6|, s92
	s_nop 1
	v_cndmask_b32_e64 v6, v6, v7, s[10:11]
	v_cndmask_b32_e32 v7, 0, v176, vcc
	v_sub_f32_e32 v6, v6, v7
	v_add_f32_e32 v0, v0, v6
	v_sub_f32_e32 v0, -0.5, v0
	v_mul_f32_e32 v0, 0x3fb8aa3b, v0
	v_exp_f32_e32 v0, v0
	s_nop 0
	v_xor_b32_e32 v0, 0x80000000, v0
	v_bfe_u32 v6, v0, 16, 1
	v_add3_u32 v0, v0, v6, s78
	v_lshl_add_u64 v[6:7], s[16:17], 0, v[2:3]
	global_store_short_d16_hi v[6:7], v0, off
	v_bfe_u32 v0, v4, 16, 1
	v_add3_u32 v0, v4, v0, s78
	v_lshl_add_u64 v[6:7], s[18:19], 0, v[2:3]
	global_store_short_d16_hi v[6:7], v0, off
	v_and_b32_e32 v0, 0xffff0000, v0
	ds_write_b32 v187, v0 offset:18112
	v_add_f32_e32 v0, v74, v13
	v_mul_f32_e64 v4, |v0|, s82
	v_exp_f32_e32 v4, v4
	v_bfe_u32 v6, v20, 16, 1
	v_add3_u32 v6, v20, v6, s78
	v_lshl_add_u64 v[2:3], s[20:21], 0, v[2:3]
	v_add_f32_e32 v4, 1.0, v4
	v_cmp_gt_f32_e32 vcc, s74, v4
	global_store_short_d16_hi v[2:3], v6, off
	v_max_f32_e64 v0, -v0, 0
	v_cndmask_b32_e64 v7, 0, 32, vcc
	v_ldexp_f32 v4, v4, v7
	v_log_f32_e32 v4, v4
	v_lshl_add_u64 v[2:3], v[146:147], 0, v[118:119]
	v_lshlrev_b64 v[2:3], 1, v[2:3]
	v_mul_f32_e32 v6, 0x3f317217, v4
	v_fma_f32 v6, v4, s83, -v6
	v_fmac_f32_e32 v6, 0x3377d1cf, v4
	v_fmac_f32_e32 v6, 0x3f317217, v4
	v_cmp_lt_f32_e64 s[10:11], |v4|, s92
	s_nop 1
	v_cndmask_b32_e64 v4, v4, v6, s[10:11]
	v_cndmask_b32_e32 v6, 0, v176, vcc
	v_sub_f32_e32 v4, v4, v6
	v_add_f32_e32 v0, v0, v4
	v_add_f32_e32 v4, v70, v5
	v_mul_f32_e32 v4, 0xbfb8aa3b, v4
	v_sub_f32_e32 v0, -0.5, v0
	v_exp_f32_e32 v4, v4
	v_mul_f32_e32 v0, 0x3fb8aa3b, v0
	v_exp_f32_e32 v0, v0
	s_cselect_b64 s[10:11], -1, 0
	v_add_f32_e32 v4, 1.0, v4
	v_rcp_f32_e32 v6, v4
	v_xor_b32_e32 v0, 0x80000000, v0
	v_bfe_u32 v5, v0, 16, 1
	v_add3_u32 v0, v0, v5, s78
	v_lshl_add_u64 v[4:5], s[16:17], 0, v[2:3]
	global_store_short_d16_hi v[4:5], v0, off
	v_bfe_u32 v0, v6, 16, 1
	v_add3_u32 v0, v6, v0, s78
	v_lshl_add_u64 v[4:5], s[18:19], 0, v[2:3]
	global_store_short_d16_hi v[4:5], v0, off
	v_and_b32_e32 v0, 0xffff0000, v0
	ds_write_b32 v188, v0 offset:18112
	v_bfe_u32 v0, v21, 16, 1
	v_add3_u32 v0, v21, v0, s78
	v_lshl_add_u64 v[2:3], s[20:21], 0, v[2:3]
	s_and_b32 s1, s35, 63
	global_store_short_d16_hi v[2:3], v0, off
	s_cmp_eq_u32 s1, 0
	s_waitcnt lgkmcnt(0)
	s_cselect_b64 s[12:13], -1, 0
	s_or_b64 s[24:25], s[10:11], s[12:13]
	s_mov_b64 s[12:13], -1
	s_and_b64 vcc, exec, s[24:25]
	s_cbranch_vccnz .LBB0_233
	s_mov_b64 s[12:13], 0
	v_lshlrev_b32_e32 v34, 16, v242
	v_lshlrev_b32_e32 v33, 16, v243

.LBB0_236:
	v_add_co_u32_e32 v2, vcc, 0x26000, v126
	s_mov_b32 s1, 0x40000
	s_nop 0
	v_addc_co_u32_e32 v3, vcc, 0, v127, vcc
	global_load_ushort v31, v[2:3], off
	global_load_ushort v32, v[2:3], off offset:1024
	v_add_co_u32_e32 v2, vcc, 0x28000, v126
	s_nop 1
	v_addc_co_u32_e32 v3, vcc, 0, v127, vcc
	global_load_ushort v29, v[2:3], off offset:1536
	global_load_ushort v30, v[2:3], off offset:2560
	v_add_co_u32_e32 v2, vcc, 0x2a000, v126
	s_nop 1
	v_addc_co_u32_e32 v3, vcc, 0, v127, vcc
	global_load_ushort v27, v[2:3], off offset:3072
	v_add_co_u32_e32 v2, vcc, 0x2b000, v126
	s_nop 1
	v_addc_co_u32_e32 v3, vcc, 0, v127, vcc
	global_load_ushort v28, v[2:3], off
	v_add_co_u32_e32 v2, vcc, 0x2d000, v126
	s_nop 1
	v_addc_co_u32_e32 v3, vcc, 0, v127, vcc
	global_load_ushort v25, v[2:3], off offset:512
	global_load_ushort v26, v[2:3], off offset:1536
	v_add_co_u32_e32 v2, vcc, 0x2f000, v126
	s_nop 1
	v_addc_co_u32_e32 v3, vcc, 0, v127, vcc
	global_load_ushort v23, v[2:3], off offset:2048
	global_load_ushort v24, v[2:3], off offset:3072
	v_add_co_u32_e32 v2, vcc, 0x31000, v126
	s_nop 1
	v_addc_co_u32_e32 v3, vcc, 0, v127, vcc
	global_load_ushort v21, v[2:3], off offset:3584
	v_add_co_u32_e32 v2, vcc, 0x32000, v126
	s_nop 1
	v_addc_co_u32_e32 v3, vcc, 0, v127, vcc
	global_load_ushort v22, v[2:3], off offset:512
	v_add_co_u32_e32 v2, vcc, 0x34000, v126
	s_nop 1
	v_addc_co_u32_e32 v3, vcc, 0, v127, vcc
	global_load_ushort v19, v[2:3], off offset:1024
	global_load_ushort v20, v[2:3], off offset:2048
	v_add_co_u32_e32 v2, vcc, 0x36000, v126
	s_nop 1
	v_addc_co_u32_e32 v3, vcc, 0, v127, vcc
	global_load_ushort v17, v[2:3], off offset:2560
	global_load_ushort v18, v[2:3], off offset:3584
	v_add_co_u32_e32 v2, vcc, 0x39000, v126
	s_nop 1
	v_addc_co_u32_e32 v3, vcc, 0, v127, vcc
	global_load_ushort v15, v[2:3], off
	global_load_ushort v16, v[2:3], off offset:1024
	v_add_co_u32_e32 v2, vcc, 0x3b000, v126
	s_nop 1
	v_addc_co_u32_e32 v3, vcc, 0, v127, vcc
	global_load_ushort v13, v[2:3], off offset:1536
	global_load_ushort v14, v[2:3], off offset:2560
	v_add_co_u32_e32 v2, vcc, 0x3d000, v126
	s_nop 1
	v_addc_co_u32_e32 v3, vcc, 0, v127, vcc
	global_load_ushort v11, v[2:3], off offset:3072
	v_add_co_u32_e32 v2, vcc, 0x3e000, v126
	s_nop 1
	v_addc_co_u32_e32 v3, vcc, 0, v127, vcc
	global_load_ushort v12, v[2:3], off
	v_add_co_u32_e32 v2, vcc, s1, v126
	s_nop 1
	v_addc_co_u32_e32 v3, vcc, 0, v127, vcc
	global_load_ushort v9, v[2:3], off offset:512
	global_load_ushort v10, v[2:3], off offset:1536
	v_add_co_u32_e32 v2, vcc, 0x42000, v126
	s_nop 1
	v_addc_co_u32_e32 v3, vcc, 0, v127, vcc
	global_load_ushort v7, v[2:3], off offset:2048
	global_load_ushort v8, v[2:3], off offset:3072
	v_add_co_u32_e32 v2, vcc, 0x44000, v126
	s_nop 1
	v_addc_co_u32_e32 v3, vcc, 0, v127, vcc
	global_load_ushort v5, v[2:3], off offset:3584
	v_add_co_u32_e32 v2, vcc, 0x45000, v126
	s_nop 1
	v_addc_co_u32_e32 v3, vcc, 0, v127, vcc
	v_add_co_u32_e32 v36, vcc, 0x47000, v126
	global_load_ushort v6, v[2:3], off offset:512
	s_nop 0
	v_addc_co_u32_e32 v37, vcc, 0, v127, vcc
	global_load_ushort v3, v[36:37], off offset:1024
	global_load_ushort v4, v[36:37], off offset:2048
	v_add_co_u32_e32 v36, vcc, 0x49000, v126
	s_nop 1
	v_addc_co_u32_e32 v37, vcc, 0, v127, vcc
	global_load_ushort v0, v[36:37], off offset:2560
	global_load_ushort v2, v[36:37], off offset:3584
	s_and_b64 vcc, exec, s[10:11]
	s_cbranch_vccnz .LBB0_238
	s_lshr_b32 s1, s34, 2
	v_mad_u64_u32 v[36:37], s[10:11], s1, v177, v[98:99]
	global_load_dword v34, v[36:37], off
	global_load_dword v33, v[36:37], off offset:2048
	s_waitcnt vmcnt(0)
.LBB0_238:
	ds_read_b32 v37, v156 offset:17920
	v_lshlrev_b32_e32 v35, 16, v220
	v_sub_f32_e32 v33, v33, v35
	v_fma_f32 v33, v151, v33, v35
	v_lshlrev_b32_e32 v36, 16, v219
	s_waitcnt lgkmcnt(0)
	v_add_f32_e32 v37, -1.0, v37
	v_mul_f32_e32 v38, v81, v33
	v_fma_f32 v37, v148, v37, 1.0
	v_sub_f32_e32 v34, v34, v36
	v_mul_f32_e32 v33, v33, v37
	v_mul_f32_e32 v37, v38, v38
	v_mov_b32_e32 v39, v1
	v_fma_f32 v34, v150, v34, v36
	v_mul_f32_e32 v33, v34, v33
	v_mov_b32_dpp v39, v37 quad_perm:[1,0,3,2] row_mask:0xf bank_mask:0xf
	v_fmac_f32_e32 v39, v38, v38
	v_mul_f32_e32 v34, v149, v33
	v_mov_b32_e32 v38, v1
	v_add_f32_dpp v37, v39, v39 quad_perm:[2,3,0,1] row_mask:0xf bank_mask:0xf bound_ctrl:1
	v_mov_b32_e32 v39, v1
	s_nop 0
	v_add_f32_dpp v37, v37, v37 row_half_mirror row_mask:0xf bank_mask:0xf bound_ctrl:1
	v_mov_b32_dpp v39, v34 quad_perm:[1,0,3,2] row_mask:0xf bank_mask:0xf
	v_fmac_f32_e32 v39, v149, v33
	v_add_f32_dpp v37, v37, v37 row_mirror row_mask:0xf bank_mask:0xf bound_ctrl:1
	v_mov_b32_e32 v34, v1
	v_add_f32_dpp v33, v39, v39 quad_perm:[2,3,0,1] row_mask:0xf bank_mask:0xf bound_ctrl:1
	v_mov_b32_dpp v38, v37 row_bcast:15 row_mask:0xa bank_mask:0xf
	v_add_f32_e32 v37, v37, v38
	v_add_f32_dpp v33, v33, v33 row_half_mirror row_mask:0xf bank_mask:0xf bound_ctrl:1
	v_mov_b32_e32 v38, v1
	s_nop 0
	v_add_f32_dpp v33, v33, v33 row_mirror row_mask:0xf bank_mask:0xf bound_ctrl:1
	v_mov_b32_dpp v38, v37 row_bcast:31 row_mask:0xc bank_mask:0xf
	s_nop 0
	v_mov_b32_dpp v34, v33 row_bcast:15 row_mask:0xa bank_mask:0xf
	v_add_f32_e32 v33, v33, v34
	v_mov_b32_e32 v34, v1
	s_nop 1
	v_mov_b32_dpp v34, v33 row_bcast:31 row_mask:0xc bank_mask:0xf
	s_and_saveexec_b64 s[12:13], s[4:5]
	s_cbranch_execz .LBB0_240
	v_add_f32_e32 v37, v37, v38
	v_mul_f32_e32 v38, 0x4f800000, v37
	v_cmp_gt_f32_e32 vcc, s93, v37
	s_ashr_i32 s1, s0, 31
	v_add_f32_e32 v33, v33, v34
	v_cndmask_b32_e32 v37, v37, v38, vcc
	v_sqrt_f32_e32 v38, v37
	s_lshl_b64 s[0:1], s[0:1], 3
	s_add_u32 s0, s0, s48
	s_addc_u32 s1, s1, 0
	v_add_u32_e32 v39, -1, v38
	v_fma_f32 v41, -v39, v38, v37
	v_add_u32_e32 v40, 1, v38
	v_cmp_ge_f32_e64 s[10:11], 0, v41
	s_lshl_b64 s[0:1], s[0:1], 2
	s_nop 0
	v_cndmask_b32_e64 v39, v38, v39, s[10:11]
	v_fma_f32 v38, -v40, v38, v37
	v_cmp_lt_f32_e64 s[10:11], 0, v38
	s_nop 1
	v_cndmask_b32_e64 v38, v39, v40, s[10:11]
	v_mul_f32_e32 v39, 0x37800000, v38
	v_cndmask_b32_e32 v38, v38, v39, vcc
	v_cmp_class_f32_e32 vcc, v37, v170
	s_nop 1
	v_cndmask_b32_e32 v37, v38, v37, vcc
	v_max_f32_e32 v37, 0x2b8cbccc, v37
	v_div_scale_f32 v38, s[10:11], v37, v37, 1.0
	v_rcp_f32_e32 v39, v38
	s_add_u32 s10, s28, s0
	s_addc_u32 s11, s29, s1
	s_add_u32 s0, s30, s0
	v_fma_f32 v34, -v38, v39, 1.0
	v_fmac_f32_e32 v39, v34, v39
	v_div_scale_f32 v34, vcc, 1.0, v37, 1.0
	v_mul_f32_e32 v40, v34, v39
	v_fma_f32 v41, -v38, v40, v34
	v_fmac_f32_e32 v40, v41, v39
	v_fma_f32 v34, -v38, v40, v34
	v_div_fmas_f32 v34, v34, v39, v40
	v_div_fixup_f32 v34, v34, v37, 1.0
	s_addc_u32 s1, s31, s1
	global_store_dword v1, v34, s[10:11]
	global_store_dword v1, v33, s[0:1]

.LBB0_246:
	s_or_b64 exec, exec, s[0:1]
	s_add_i32 s0, s34, 0x4004
	s_cmpk_lt_i32 s0, 0x4000
	s_cbranch_scc1 .LBB0_248
	s_add_i32 s1, s34, 4
	s_lshr_b32 s1, s1, 2
	v_mad_u64_u32 v[36:37], s[10:11], s1, v177, v[98:99]
	global_load_dword v34, v[36:37], off
	global_load_dword v33, v[36:37], off offset:2048
	s_waitcnt vmcnt(0)
.LBB0_248:
	ds_read_b32 v37, v156 offset:18944
	v_lshlrev_b32_e32 v35, 16, v212
	v_sub_f32_e32 v33, v33, v35
	v_fma_f32 v33, v151, v33, v35
	v_lshlrev_b32_e32 v36, 16, v211
	s_waitcnt lgkmcnt(0)
	v_add_f32_e32 v37, -1.0, v37
	v_mul_f32_e32 v38, v81, v33
	v_fma_f32 v37, v148, v37, 1.0
	v_sub_f32_e32 v34, v34, v36
	v_mul_f32_e32 v33, v33, v37
	v_mul_f32_e32 v37, v38, v38
	v_mov_b32_e32 v39, v1
	v_fma_f32 v34, v150, v34, v36
	v_mul_f32_e32 v33, v34, v33
	v_mov_b32_dpp v39, v37 quad_perm:[1,0,3,2] row_mask:0xf bank_mask:0xf
	v_fmac_f32_e32 v39, v38, v38
	v_mul_f32_e32 v34, v149, v33
	v_mov_b32_e32 v38, v1
	v_add_f32_dpp v37, v39, v39 quad_perm:[2,3,0,1] row_mask:0xf bank_mask:0xf bound_ctrl:1
	v_mov_b32_e32 v39, v1
	s_mov_b32 s24, s53
	v_add_f32_dpp v37, v37, v37 row_half_mirror row_mask:0xf bank_mask:0xf bound_ctrl:1
	v_mov_b32_dpp v39, v34 quad_perm:[1,0,3,2] row_mask:0xf bank_mask:0xf
	v_fmac_f32_e32 v39, v149, v33
	v_add_f32_dpp v37, v37, v37 row_mirror row_mask:0xf bank_mask:0xf bound_ctrl:1
	v_mov_b32_e32 v34, v1
	v_add_f32_dpp v33, v39, v39 quad_perm:[2,3,0,1] row_mask:0xf bank_mask:0xf bound_ctrl:1
	v_mov_b32_dpp v38, v37 row_bcast:15 row_mask:0xa bank_mask:0xf
	v_add_f32_e32 v37, v37, v38
	v_add_f32_dpp v33, v33, v33 row_half_mirror row_mask:0xf bank_mask:0xf bound_ctrl:1
	v_mov_b32_e32 v38, v1
	s_nop 0
	v_add_f32_dpp v33, v33, v33 row_mirror row_mask:0xf bank_mask:0xf bound_ctrl:1
	v_mov_b32_dpp v38, v37 row_bcast:31 row_mask:0xc bank_mask:0xf
	s_nop 0
	v_mov_b32_dpp v34, v33 row_bcast:15 row_mask:0xa bank_mask:0xf
	v_add_f32_e32 v33, v33, v34
	v_mov_b32_e32 v34, v1
	s_nop 1
	v_mov_b32_dpp v34, v33 row_bcast:31 row_mask:0xc bank_mask:0xf
	s_and_saveexec_b64 s[12:13], s[4:5]
	s_cbranch_execz .LBB0_250
	v_add_f32_e32 v37, v37, v38
	v_mul_f32_e32 v38, 0x4f800000, v37
	v_cmp_gt_f32_e32 vcc, s93, v37
	s_ashr_i32 s1, s0, 31
	v_add_f32_e32 v33, v33, v34
	v_cndmask_b32_e32 v37, v37, v38, vcc
	v_sqrt_f32_e32 v38, v37
	s_lshl_b64 s[0:1], s[0:1], 3
	s_add_u32 s0, s0, s48
	s_addc_u32 s1, s1, 0
	v_add_u32_e32 v39, -1, v38
	v_fma_f32 v41, -v39, v38, v37
	v_add_u32_e32 v40, 1, v38
	v_cmp_ge_f32_e64 s[10:11], 0, v41
	s_lshl_b64 s[0:1], s[0:1], 2
	s_mov_b32 s24, s53
	v_cndmask_b32_e64 v39, v38, v39, s[10:11]
	v_fma_f32 v38, -v40, v38, v37
	v_cmp_lt_f32_e64 s[10:11], 0, v38
	s_nop 1
	v_cndmask_b32_e64 v38, v39, v40, s[10:11]
	v_mul_f32_e32 v39, 0x37800000, v38
	v_cndmask_b32_e32 v38, v38, v39, vcc
	v_cmp_class_f32_e32 vcc, v37, v170
	s_nop 1
	v_cndmask_b32_e32 v37, v38, v37, vcc
	v_max_f32_e32 v37, 0x2b8cbccc, v37
	v_div_scale_f32 v38, s[10:11], v37, v37, 1.0
	v_rcp_f32_e32 v39, v38
	s_add_u32 s10, s28, s0
	s_addc_u32 s11, s29, s1
	s_add_u32 s0, s30, s0
	v_fma_f32 v34, -v38, v39, 1.0
	v_fmac_f32_e32 v39, v34, v39
	v_div_scale_f32 v34, vcc, 1.0, v37, 1.0
	v_mul_f32_e32 v40, v34, v39
	v_fma_f32 v41, -v38, v40, v34
	v_fmac_f32_e32 v40, v41, v39
	v_fma_f32 v34, -v38, v40, v34
	v_div_fmas_f32 v34, v34, v39, v40
	v_div_fixup_f32 v34, v34, v37, 1.0
	s_addc_u32 s1, s31, s1
	global_store_dword v1, v34, s[10:11]
	global_store_dword v1, v33, s[0:1]

.LBB0_256:
	s_or_b64 exec, exec, s[0:1]
	s_add_i32 s0, s34, 0x4008
	s_cmpk_lt_i32 s0, 0x4000
	s_cbranch_scc1 .LBB0_258
	s_add_i32 s1, s34, 8
	s_lshr_b32 s1, s1, 2
	v_mad_u64_u32 v[36:37], s[10:11], s1, v177, v[98:99]
	global_load_dword v34, v[36:37], off
	global_load_dword v33, v[36:37], off offset:2048
	s_waitcnt vmcnt(0)
.LBB0_258:
	ds_read_b32 v37, v156 offset:19968
	v_lshlrev_b32_e32 v35, 16, v204
	v_sub_f32_e32 v33, v33, v35
	v_fma_f32 v33, v151, v33, v35
	v_lshlrev_b32_e32 v36, 16, v203
	s_waitcnt lgkmcnt(0)
	v_add_f32_e32 v37, -1.0, v37
	v_mul_f32_e32 v38, v81, v33
	v_fma_f32 v37, v148, v37, 1.0
	v_sub_f32_e32 v34, v34, v36
	v_mul_f32_e32 v33, v33, v37
	v_mul_f32_e32 v37, v38, v38
	v_mov_b32_e32 v39, v1
	v_fma_f32 v34, v150, v34, v36
	v_mul_f32_e32 v33, v34, v33
	v_mov_b32_dpp v39, v37 quad_perm:[1,0,3,2] row_mask:0xf bank_mask:0xf
	v_fmac_f32_e32 v39, v38, v38
	v_mul_f32_e32 v34, v149, v33
	v_mov_b32_e32 v38, v1
	v_add_f32_dpp v37, v39, v39 quad_perm:[2,3,0,1] row_mask:0xf bank_mask:0xf bound_ctrl:1
	v_mov_b32_e32 v39, v1
	s_nop 0
	v_add_f32_dpp v37, v37, v37 row_half_mirror row_mask:0xf bank_mask:0xf bound_ctrl:1
	v_mov_b32_dpp v39, v34 quad_perm:[1,0,3,2] row_mask:0xf bank_mask:0xf
	v_fmac_f32_e32 v39, v149, v33
	v_add_f32_dpp v37, v37, v37 row_mirror row_mask:0xf bank_mask:0xf bound_ctrl:1
	v_mov_b32_e32 v34, v1
	v_add_f32_dpp v33, v39, v39 quad_perm:[2,3,0,1] row_mask:0xf bank_mask:0xf bound_ctrl:1
	v_mov_b32_dpp v38, v37 row_bcast:15 row_mask:0xa bank_mask:0xf
	v_add_f32_e32 v37, v37, v38
	v_add_f32_dpp v33, v33, v33 row_half_mirror row_mask:0xf bank_mask:0xf bound_ctrl:1
	v_mov_b32_e32 v38, v1
	s_nop 0
	v_add_f32_dpp v33, v33, v33 row_mirror row_mask:0xf bank_mask:0xf bound_ctrl:1
	v_mov_b32_dpp v38, v37 row_bcast:31 row_mask:0xc bank_mask:0xf
	s_nop 0
	v_mov_b32_dpp v34, v33 row_bcast:15 row_mask:0xa bank_mask:0xf
	v_add_f32_e32 v33, v33, v34
	v_mov_b32_e32 v34, v1
	s_nop 1
	v_mov_b32_dpp v34, v33 row_bcast:31 row_mask:0xc bank_mask:0xf
	s_and_saveexec_b64 s[12:13], s[4:5]
	s_cbranch_execz .LBB0_260
	v_add_f32_e32 v37, v37, v38
	v_mul_f32_e32 v38, 0x4f800000, v37
	v_cmp_gt_f32_e32 vcc, s93, v37
	s_ashr_i32 s1, s0, 31
	v_add_f32_e32 v33, v33, v34
	v_cndmask_b32_e32 v37, v37, v38, vcc
	v_sqrt_f32_e32 v38, v37
	s_lshl_b64 s[0:1], s[0:1], 3
	s_add_u32 s0, s0, s48
	s_addc_u32 s1, s1, 0
	v_add_u32_e32 v39, -1, v38
	v_fma_f32 v41, -v39, v38, v37
	v_add_u32_e32 v40, 1, v38
	v_cmp_ge_f32_e64 s[10:11], 0, v41
	s_lshl_b64 s[0:1], s[0:1], 2
	s_mov_b32 s24, s53
	v_cndmask_b32_e64 v39, v38, v39, s[10:11]
	v_fma_f32 v38, -v40, v38, v37
	v_cmp_lt_f32_e64 s[10:11], 0, v38
	s_nop 1
	v_cndmask_b32_e64 v38, v39, v40, s[10:11]
	v_mul_f32_e32 v39, 0x37800000, v38
	v_cndmask_b32_e32 v38, v38, v39, vcc
	v_cmp_class_f32_e32 vcc, v37, v170
	s_nop 1
	v_cndmask_b32_e32 v37, v38, v37, vcc
	v_max_f32_e32 v37, 0x2b8cbccc, v37
	v_div_scale_f32 v38, s[10:11], v37, v37, 1.0
	v_rcp_f32_e32 v39, v38
	s_add_u32 s10, s28, s0
	s_addc_u32 s11, s29, s1
	s_add_u32 s0, s30, s0
	v_fma_f32 v34, -v38, v39, 1.0
	v_fmac_f32_e32 v39, v34, v39
	v_div_scale_f32 v34, vcc, 1.0, v37, 1.0
	v_mul_f32_e32 v40, v34, v39
	v_fma_f32 v41, -v38, v40, v34
	v_fmac_f32_e32 v40, v41, v39
	v_fma_f32 v34, -v38, v40, v34
	v_div_fmas_f32 v34, v34, v39, v40
	v_div_fixup_f32 v34, v34, v37, 1.0
	s_addc_u32 s1, s31, s1
	global_store_dword v1, v34, s[10:11]
	global_store_dword v1, v33, s[0:1]

.LBB0_266:
	s_or_b64 exec, exec, s[0:1]
	s_add_i32 s0, s34, 0x400c
	s_cmpk_lt_i32 s0, 0x4000
	s_cbranch_scc1 .LBB0_268
	s_add_i32 s1, s34, 12
	s_lshr_b32 s1, s1, 2
	v_mad_u64_u32 v[36:37], s[10:11], s1, v177, v[98:99]
	global_load_dword v34, v[36:37], off
	global_load_dword v33, v[36:37], off offset:2048
	s_waitcnt vmcnt(0)
.LBB0_268:
	ds_read_b32 v37, v156 offset:20992
	v_lshlrev_b32_e32 v35, 16, v196
	v_sub_f32_e32 v33, v33, v35
	v_fma_f32 v33, v151, v33, v35
	v_lshlrev_b32_e32 v36, 16, v195
	s_waitcnt lgkmcnt(0)
	v_add_f32_e32 v37, -1.0, v37
	v_mul_f32_e32 v38, v81, v33
	v_fma_f32 v37, v148, v37, 1.0
	v_sub_f32_e32 v34, v34, v36
	v_mul_f32_e32 v33, v33, v37
	v_mul_f32_e32 v37, v38, v38
	v_mov_b32_e32 v39, v1
	v_fma_f32 v34, v150, v34, v36
	v_mul_f32_e32 v33, v34, v33
	v_mov_b32_dpp v39, v37 quad_perm:[1,0,3,2] row_mask:0xf bank_mask:0xf
	v_fmac_f32_e32 v39, v38, v38
	v_mul_f32_e32 v34, v149, v33
	v_mov_b32_e32 v38, v1
	v_add_f32_dpp v37, v39, v39 quad_perm:[2,3,0,1] row_mask:0xf bank_mask:0xf bound_ctrl:1
	v_mov_b32_e32 v39, v1
	s_nop 0
	v_add_f32_dpp v37, v37, v37 row_half_mirror row_mask:0xf bank_mask:0xf bound_ctrl:1
	v_mov_b32_dpp v39, v34 quad_perm:[1,0,3,2] row_mask:0xf bank_mask:0xf
	v_fmac_f32_e32 v39, v149, v33
	v_add_f32_dpp v37, v37, v37 row_mirror row_mask:0xf bank_mask:0xf bound_ctrl:1
	v_mov_b32_e32 v34, v1
	v_add_f32_dpp v33, v39, v39 quad_perm:[2,3,0,1] row_mask:0xf bank_mask:0xf bound_ctrl:1
	v_mov_b32_dpp v38, v37 row_bcast:15 row_mask:0xa bank_mask:0xf
	v_add_f32_e32 v37, v37, v38
	v_add_f32_dpp v33, v33, v33 row_half_mirror row_mask:0xf bank_mask:0xf bound_ctrl:1
	v_mov_b32_e32 v38, v1
	s_nop 0
	v_add_f32_dpp v33, v33, v33 row_mirror row_mask:0xf bank_mask:0xf bound_ctrl:1
	v_mov_b32_dpp v38, v37 row_bcast:31 row_mask:0xc bank_mask:0xf
	s_nop 0
	v_mov_b32_dpp v34, v33 row_bcast:15 row_mask:0xa bank_mask:0xf
	v_add_f32_e32 v33, v33, v34
	v_mov_b32_e32 v34, v1
	s_nop 1
	v_mov_b32_dpp v34, v33 row_bcast:31 row_mask:0xc bank_mask:0xf
	s_and_saveexec_b64 s[12:13], s[4:5]
	s_cbranch_execz .LBB0_270
	v_add_f32_e32 v37, v37, v38
	v_mul_f32_e32 v38, 0x4f800000, v37
	v_cmp_gt_f32_e32 vcc, s93, v37
	s_ashr_i32 s1, s0, 31
	v_add_f32_e32 v33, v33, v34
	v_cndmask_b32_e32 v37, v37, v38, vcc
	v_sqrt_f32_e32 v38, v37
	s_lshl_b64 s[0:1], s[0:1], 3
	s_add_u32 s0, s0, s48
	s_addc_u32 s1, s1, 0
	v_add_u32_e32 v39, -1, v38
	v_fma_f32 v41, -v39, v38, v37
	v_add_u32_e32 v40, 1, v38
	v_cmp_ge_f32_e64 s[10:11], 0, v41
	s_lshl_b64 s[0:1], s[0:1], 2
	s_mov_b32 s24, s53
	v_cndmask_b32_e64 v39, v38, v39, s[10:11]
	v_fma_f32 v38, -v40, v38, v37
	v_cmp_lt_f32_e64 s[10:11], 0, v38
	s_nop 1
	v_cndmask_b32_e64 v38, v39, v40, s[10:11]
	v_mul_f32_e32 v39, 0x37800000, v38
	v_cndmask_b32_e32 v38, v38, v39, vcc
	v_cmp_class_f32_e32 vcc, v37, v170
	s_nop 1
	v_cndmask_b32_e32 v37, v38, v37, vcc
	v_max_f32_e32 v37, 0x2b8cbccc, v37
	v_div_scale_f32 v38, s[10:11], v37, v37, 1.0
	v_rcp_f32_e32 v39, v38
	s_add_u32 s10, s28, s0
	s_addc_u32 s11, s29, s1
	s_add_u32 s0, s30, s0
	v_fma_f32 v34, -v38, v39, 1.0
	v_fmac_f32_e32 v39, v34, v39
	v_div_scale_f32 v34, vcc, 1.0, v37, 1.0
	v_mul_f32_e32 v40, v34, v39
	v_fma_f32 v41, -v38, v40, v34
	v_fmac_f32_e32 v40, v41, v39
	v_fma_f32 v34, -v38, v40, v34
	v_div_fmas_f32 v34, v34, v39, v40
	v_div_fixup_f32 v34, v34, v37, 1.0
	s_addc_u32 s1, s31, s1
	global_store_dword v1, v34, s[10:11]
	global_store_dword v1, v33, s[0:1]

.LBB0_276:
	s_or_b64 exec, exec, s[0:1]
	s_add_i32 s0, s34, 0x4010
	s_cmpk_lt_i32 s0, 0x4000
	s_cbranch_scc1 .LBB0_278
	s_add_i32 s1, s34, 16
	s_lshr_b32 s1, s1, 2
	v_mad_u64_u32 v[36:37], s[10:11], s1, v177, v[98:99]
	global_load_dword v34, v[36:37], off
	global_load_dword v33, v[36:37], off offset:2048
	s_waitcnt vmcnt(0)
.LBB0_278:
	s_waitcnt vmcnt(32)
	ds_read_b32 v35, v156 offset:22016
	v_lshlrev_b32_e32 v32, 16, v32
	v_sub_f32_e32 v33, v33, v32
	v_fma_f32 v33, v151, v33, v32
	v_lshlrev_b32_e32 v31, 16, v31
	s_waitcnt lgkmcnt(0)
	v_add_f32_e32 v35, -1.0, v35
	v_mul_f32_e32 v36, v81, v33
	v_fma_f32 v35, v148, v35, 1.0
	v_sub_f32_e32 v34, v34, v31
	v_mul_f32_e32 v33, v33, v35
	v_mul_f32_e32 v35, v36, v36
	v_mov_b32_e32 v37, v1
	v_fma_f32 v34, v150, v34, v31
	v_mul_f32_e32 v33, v34, v33
	v_mov_b32_dpp v37, v35 quad_perm:[1,0,3,2] row_mask:0xf bank_mask:0xf
	v_fmac_f32_e32 v37, v36, v36
	v_mul_f32_e32 v34, v149, v33
	v_mov_b32_e32 v36, v1
	v_add_f32_dpp v35, v37, v37 quad_perm:[2,3,0,1] row_mask:0xf bank_mask:0xf bound_ctrl:1
	v_mov_b32_e32 v37, v1
	s_nop 0
	v_add_f32_dpp v35, v35, v35 row_half_mirror row_mask:0xf bank_mask:0xf bound_ctrl:1
	v_mov_b32_dpp v37, v34 quad_perm:[1,0,3,2] row_mask:0xf bank_mask:0xf
	v_fmac_f32_e32 v37, v149, v33
	v_add_f32_dpp v35, v35, v35 row_mirror row_mask:0xf bank_mask:0xf bound_ctrl:1
	v_mov_b32_e32 v34, v1
	v_add_f32_dpp v33, v37, v37 quad_perm:[2,3,0,1] row_mask:0xf bank_mask:0xf bound_ctrl:1
	v_mov_b32_dpp v36, v35 row_bcast:15 row_mask:0xa bank_mask:0xf
	v_add_f32_e32 v35, v35, v36
	v_add_f32_dpp v33, v33, v33 row_half_mirror row_mask:0xf bank_mask:0xf bound_ctrl:1
	v_mov_b32_e32 v36, v1
	s_nop 0
	v_add_f32_dpp v33, v33, v33 row_mirror row_mask:0xf bank_mask:0xf bound_ctrl:1
	v_mov_b32_dpp v36, v35 row_bcast:31 row_mask:0xc bank_mask:0xf
	s_nop 0
	v_mov_b32_dpp v34, v33 row_bcast:15 row_mask:0xa bank_mask:0xf
	v_add_f32_e32 v33, v33, v34
	v_mov_b32_e32 v34, v1
	s_nop 1
	v_mov_b32_dpp v34, v33 row_bcast:31 row_mask:0xc bank_mask:0xf
	s_and_saveexec_b64 s[12:13], s[4:5]
	s_cbranch_execz .LBB0_280
	v_add_f32_e32 v35, v35, v36
	v_mul_f32_e32 v36, 0x4f800000, v35
	v_cmp_gt_f32_e32 vcc, s93, v35
	s_ashr_i32 s1, s0, 31
	v_add_f32_e32 v33, v33, v34
	v_cndmask_b32_e32 v35, v35, v36, vcc
	v_sqrt_f32_e32 v36, v35
	s_lshl_b64 s[0:1], s[0:1], 3
	s_add_u32 s0, s0, s48
	s_addc_u32 s1, s1, 0
	v_add_u32_e32 v37, -1, v36
	v_fma_f32 v39, -v37, v36, v35
	v_add_u32_e32 v38, 1, v36
	v_cmp_ge_f32_e64 s[10:11], 0, v39
	s_lshl_b64 s[0:1], s[0:1], 2
	s_mov_b32 s24, s53
	v_cndmask_b32_e64 v37, v36, v37, s[10:11]
	v_fma_f32 v36, -v38, v36, v35
	v_cmp_lt_f32_e64 s[10:11], 0, v36
	s_nop 1
	v_cndmask_b32_e64 v36, v37, v38, s[10:11]
	v_mul_f32_e32 v37, 0x37800000, v36
	v_cndmask_b32_e32 v36, v36, v37, vcc
	v_cmp_class_f32_e32 vcc, v35, v170
	s_nop 1
	v_cndmask_b32_e32 v35, v36, v35, vcc
	v_max_f32_e32 v35, 0x2b8cbccc, v35
	v_div_scale_f32 v36, s[10:11], v35, v35, 1.0
	v_rcp_f32_e32 v37, v36
	s_add_u32 s10, s28, s0
	s_addc_u32 s11, s29, s1
	s_add_u32 s0, s30, s0
	v_fma_f32 v34, -v36, v37, 1.0
	v_fmac_f32_e32 v37, v34, v37
	v_div_scale_f32 v34, vcc, 1.0, v35, 1.0
	v_mul_f32_e32 v38, v34, v37
	v_fma_f32 v39, -v36, v38, v34
	v_fmac_f32_e32 v38, v39, v37
	v_fma_f32 v34, -v36, v38, v34
	v_div_fmas_f32 v34, v34, v37, v38
	v_div_fixup_f32 v34, v34, v35, 1.0
	s_addc_u32 s1, s31, s1
	global_store_dword v1, v34, s[10:11]
	global_store_dword v1, v33, s[0:1]

.LBB0_286:
	s_or_b64 exec, exec, s[0:1]
	s_add_i32 s0, s34, 0x4014
	s_cmpk_lt_i32 s0, 0x4000
	s_cbranch_scc1 .LBB0_288
	s_add_i32 s1, s34, 20
	s_lshr_b32 s1, s1, 2
	v_mad_u64_u32 v[26:27], s[10:11], s1, v177, v[98:99]
	global_load_dword v25, v[26:27], off
	s_nop 0
	global_load_dword v26, v[26:27], off offset:2048
	s_waitcnt vmcnt(0)
.LBB0_288:
	ds_read_b32 v27, v156 offset:23040
	v_lshlrev_b32_e32 v24, 16, v24
	v_sub_f32_e32 v26, v26, v24
	v_fma_f32 v26, v151, v26, v24
	v_lshlrev_b32_e32 v23, 16, v23
	s_waitcnt lgkmcnt(0)
	v_add_f32_e32 v27, -1.0, v27
	v_mul_f32_e32 v28, v81, v26
	v_fma_f32 v27, v148, v27, 1.0
	v_sub_f32_e32 v25, v25, v23
	v_mul_f32_e32 v26, v26, v27
	v_mul_f32_e32 v27, v28, v28
	v_mov_b32_e32 v29, v1
	v_fma_f32 v25, v150, v25, v23
	v_mul_f32_e32 v25, v25, v26
	v_mov_b32_dpp v29, v27 quad_perm:[1,0,3,2] row_mask:0xf bank_mask:0xf
	v_fmac_f32_e32 v29, v28, v28
	v_mul_f32_e32 v26, v149, v25
	v_mov_b32_e32 v28, v1
	v_add_f32_dpp v27, v29, v29 quad_perm:[2,3,0,1] row_mask:0xf bank_mask:0xf bound_ctrl:1
	v_mov_b32_e32 v29, v1
	s_nop 0
	v_add_f32_dpp v27, v27, v27 row_half_mirror row_mask:0xf bank_mask:0xf bound_ctrl:1
	v_mov_b32_dpp v29, v26 quad_perm:[1,0,3,2] row_mask:0xf bank_mask:0xf
	v_fmac_f32_e32 v29, v149, v25
	v_add_f32_dpp v27, v27, v27 row_mirror row_mask:0xf bank_mask:0xf bound_ctrl:1
	v_mov_b32_e32 v26, v1
	v_add_f32_dpp v25, v29, v29 quad_perm:[2,3,0,1] row_mask:0xf bank_mask:0xf bound_ctrl:1
	v_mov_b32_dpp v28, v27 row_bcast:15 row_mask:0xa bank_mask:0xf
	v_add_f32_e32 v27, v27, v28
	v_add_f32_dpp v25, v25, v25 row_half_mirror row_mask:0xf bank_mask:0xf bound_ctrl:1
	v_mov_b32_e32 v28, v1
	s_nop 0
	v_add_f32_dpp v25, v25, v25 row_mirror row_mask:0xf bank_mask:0xf bound_ctrl:1
	v_mov_b32_dpp v28, v27 row_bcast:31 row_mask:0xc bank_mask:0xf
	s_nop 0
	v_mov_b32_dpp v26, v25 row_bcast:15 row_mask:0xa bank_mask:0xf
	v_add_f32_e32 v25, v25, v26
	v_mov_b32_e32 v26, v1
	s_nop 1
	v_mov_b32_dpp v26, v25 row_bcast:31 row_mask:0xc bank_mask:0xf
	s_and_saveexec_b64 s[12:13], s[4:5]
	s_cbranch_execz .LBB0_290
	v_add_f32_e32 v27, v27, v28
	v_mul_f32_e32 v28, 0x4f800000, v27
	v_cmp_gt_f32_e32 vcc, s93, v27
	s_ashr_i32 s1, s0, 31
	v_add_f32_e32 v25, v25, v26
	v_cndmask_b32_e32 v27, v27, v28, vcc
	v_sqrt_f32_e32 v28, v27
	s_lshl_b64 s[0:1], s[0:1], 3
	s_add_u32 s0, s0, s48
	s_addc_u32 s1, s1, 0
	v_add_u32_e32 v29, -1, v28
	v_fma_f32 v31, -v29, v28, v27
	v_add_u32_e32 v30, 1, v28
	v_cmp_ge_f32_e64 s[10:11], 0, v31
	s_lshl_b64 s[0:1], s[0:1], 2
	s_mov_b32 s24, s53
	v_cndmask_b32_e64 v29, v28, v29, s[10:11]
	v_fma_f32 v28, -v30, v28, v27
	v_cmp_lt_f32_e64 s[10:11], 0, v28
	s_nop 1
	v_cndmask_b32_e64 v28, v29, v30, s[10:11]
	v_mul_f32_e32 v29, 0x37800000, v28
	v_cndmask_b32_e32 v28, v28, v29, vcc
	v_cmp_class_f32_e32 vcc, v27, v170
	s_nop 1
	v_cndmask_b32_e32 v27, v28, v27, vcc
	v_max_f32_e32 v27, 0x2b8cbccc, v27
	v_div_scale_f32 v28, s[10:11], v27, v27, 1.0
	v_rcp_f32_e32 v29, v28
	s_add_u32 s10, s28, s0
	s_addc_u32 s11, s29, s1
	s_add_u32 s0, s30, s0
	v_fma_f32 v26, -v28, v29, 1.0
	v_fmac_f32_e32 v29, v26, v29
	v_div_scale_f32 v26, vcc, 1.0, v27, 1.0
	v_mul_f32_e32 v30, v26, v29
	v_fma_f32 v31, -v28, v30, v26
	v_fmac_f32_e32 v30, v31, v29
	v_fma_f32 v26, -v28, v30, v26
	v_div_fmas_f32 v26, v26, v29, v30
	v_div_fixup_f32 v26, v26, v27, 1.0
	s_addc_u32 s1, s31, s1
	global_store_dword v1, v26, s[10:11]
	global_store_dword v1, v25, s[0:1]

.LBB0_296:
	s_or_b64 exec, exec, s[0:1]
	s_add_i32 s0, s34, 0x4018
	s_cmpk_lt_i32 s0, 0x4000
	s_cbranch_scc1 .LBB0_298
	s_add_i32 s1, s34, 24
	s_lshr_b32 s1, s1, 2
	v_mad_u64_u32 v[18:19], s[10:11], s1, v177, v[98:99]
	global_load_dword v17, v[18:19], off
	s_nop 0
	global_load_dword v18, v[18:19], off offset:2048
	s_waitcnt vmcnt(0)
.LBB0_298:
	ds_read_b32 v19, v156 offset:24064
	v_lshlrev_b32_e32 v16, 16, v16
	v_sub_f32_e32 v18, v18, v16
	v_fma_f32 v18, v151, v18, v16
	v_lshlrev_b32_e32 v15, 16, v15
	s_waitcnt lgkmcnt(0)
	v_add_f32_e32 v19, -1.0, v19
	v_mul_f32_e32 v20, v81, v18
	v_fma_f32 v19, v148, v19, 1.0
	v_sub_f32_e32 v17, v17, v15
	v_mul_f32_e32 v18, v18, v19
	v_mul_f32_e32 v19, v20, v20
	v_mov_b32_e32 v21, v1
	v_fma_f32 v17, v150, v17, v15
	v_mul_f32_e32 v17, v17, v18
	v_mov_b32_dpp v21, v19 quad_perm:[1,0,3,2] row_mask:0xf bank_mask:0xf
	v_fmac_f32_e32 v21, v20, v20
	v_mul_f32_e32 v18, v149, v17
	v_mov_b32_e32 v20, v1
	v_add_f32_dpp v19, v21, v21 quad_perm:[2,3,0,1] row_mask:0xf bank_mask:0xf bound_ctrl:1
	v_mov_b32_e32 v21, v1
	s_nop 0
	v_add_f32_dpp v19, v19, v19 row_half_mirror row_mask:0xf bank_mask:0xf bound_ctrl:1
	v_mov_b32_dpp v21, v18 quad_perm:[1,0,3,2] row_mask:0xf bank_mask:0xf
	v_fmac_f32_e32 v21, v149, v17
	v_add_f32_dpp v19, v19, v19 row_mirror row_mask:0xf bank_mask:0xf bound_ctrl:1
	v_mov_b32_e32 v18, v1
	v_add_f32_dpp v17, v21, v21 quad_perm:[2,3,0,1] row_mask:0xf bank_mask:0xf bound_ctrl:1
	v_mov_b32_dpp v20, v19 row_bcast:15 row_mask:0xa bank_mask:0xf
	v_add_f32_e32 v19, v19, v20
	v_add_f32_dpp v17, v17, v17 row_half_mirror row_mask:0xf bank_mask:0xf bound_ctrl:1
	v_mov_b32_e32 v20, v1
	s_nop 0
	v_add_f32_dpp v17, v17, v17 row_mirror row_mask:0xf bank_mask:0xf bound_ctrl:1
	v_mov_b32_dpp v20, v19 row_bcast:31 row_mask:0xc bank_mask:0xf
	s_nop 0
	v_mov_b32_dpp v18, v17 row_bcast:15 row_mask:0xa bank_mask:0xf
	v_add_f32_e32 v17, v17, v18
	v_mov_b32_e32 v18, v1
	s_nop 1
	v_mov_b32_dpp v18, v17 row_bcast:31 row_mask:0xc bank_mask:0xf
	s_and_saveexec_b64 s[12:13], s[4:5]
	s_cbranch_execz .LBB0_300
	v_add_f32_e32 v19, v19, v20
	v_mul_f32_e32 v20, 0x4f800000, v19
	v_cmp_gt_f32_e32 vcc, s93, v19
	s_ashr_i32 s1, s0, 31
	v_add_f32_e32 v17, v17, v18
	v_cndmask_b32_e32 v19, v19, v20, vcc
	v_sqrt_f32_e32 v20, v19
	s_lshl_b64 s[0:1], s[0:1], 3
	s_add_u32 s0, s0, s48
	s_addc_u32 s1, s1, 0
	v_add_u32_e32 v21, -1, v20
	v_fma_f32 v23, -v21, v20, v19
	v_add_u32_e32 v22, 1, v20
	v_cmp_ge_f32_e64 s[10:11], 0, v23
	s_lshl_b64 s[0:1], s[0:1], 2
	s_mov_b32 s24, s53
	v_cndmask_b32_e64 v21, v20, v21, s[10:11]
	v_fma_f32 v20, -v22, v20, v19
	v_cmp_lt_f32_e64 s[10:11], 0, v20
	s_nop 1
	v_cndmask_b32_e64 v20, v21, v22, s[10:11]
	v_mul_f32_e32 v21, 0x37800000, v20
	v_cndmask_b32_e32 v20, v20, v21, vcc
	v_cmp_class_f32_e32 vcc, v19, v170
	s_nop 1
	v_cndmask_b32_e32 v19, v20, v19, vcc
	v_max_f32_e32 v19, 0x2b8cbccc, v19
	v_div_scale_f32 v20, s[10:11], v19, v19, 1.0
	v_rcp_f32_e32 v21, v20
	s_add_u32 s10, s28, s0
	s_addc_u32 s11, s29, s1
	s_add_u32 s0, s30, s0
	v_fma_f32 v18, -v20, v21, 1.0
	v_fmac_f32_e32 v21, v18, v21
	v_div_scale_f32 v18, vcc, 1.0, v19, 1.0
	v_mul_f32_e32 v22, v18, v21
	v_fma_f32 v23, -v20, v22, v18
	v_fmac_f32_e32 v22, v23, v21
	v_fma_f32 v18, -v20, v22, v18
	v_div_fmas_f32 v18, v18, v21, v22
	v_div_fixup_f32 v18, v18, v19, 1.0
	s_addc_u32 s1, s31, s1
	global_store_dword v1, v18, s[10:11]
	global_store_dword v1, v17, s[0:1]

.LBB0_306:
	s_or_b64 exec, exec, s[0:1]
	s_add_i32 s0, s34, 0x401c
	s_cmpk_lt_i32 s0, 0x4000
	s_cbranch_scc1 .LBB0_308
	s_add_i32 s1, s34, 28
	s_lshr_b32 s1, s1, 2
	v_mad_u64_u32 v[10:11], s[10:11], s1, v177, v[98:99]
	global_load_dword v9, v[10:11], off
	s_nop 0
	global_load_dword v10, v[10:11], off offset:2048
	s_waitcnt vmcnt(0)
.LBB0_308:
	ds_read_b32 v11, v156 offset:25088
	v_lshlrev_b32_e32 v8, 16, v8
	v_sub_f32_e32 v10, v10, v8
	v_fma_f32 v10, v151, v10, v8
	v_lshlrev_b32_e32 v7, 16, v7
	s_waitcnt lgkmcnt(0)
	v_add_f32_e32 v11, -1.0, v11
	v_mul_f32_e32 v12, v81, v10
	v_fma_f32 v11, v148, v11, 1.0
	v_sub_f32_e32 v9, v9, v7
	v_mul_f32_e32 v10, v10, v11
	v_mul_f32_e32 v11, v12, v12
	v_mov_b32_e32 v13, v1
	v_fma_f32 v9, v150, v9, v7
	v_mul_f32_e32 v9, v9, v10
	v_mov_b32_dpp v13, v11 quad_perm:[1,0,3,2] row_mask:0xf bank_mask:0xf
	v_fmac_f32_e32 v13, v12, v12
	v_mul_f32_e32 v10, v149, v9
	v_mov_b32_e32 v12, v1
	v_add_f32_dpp v11, v13, v13 quad_perm:[2,3,0,1] row_mask:0xf bank_mask:0xf bound_ctrl:1
	v_mov_b32_e32 v13, v1
	s_nop 0
	v_add_f32_dpp v11, v11, v11 row_half_mirror row_mask:0xf bank_mask:0xf bound_ctrl:1
	v_mov_b32_dpp v13, v10 quad_perm:[1,0,3,2] row_mask:0xf bank_mask:0xf
	v_fmac_f32_e32 v13, v149, v9
	v_add_f32_dpp v11, v11, v11 row_mirror row_mask:0xf bank_mask:0xf bound_ctrl:1
	v_mov_b32_e32 v10, v1
	v_add_f32_dpp v9, v13, v13 quad_perm:[2,3,0,1] row_mask:0xf bank_mask:0xf bound_ctrl:1
	v_mov_b32_dpp v12, v11 row_bcast:15 row_mask:0xa bank_mask:0xf
	v_add_f32_e32 v11, v11, v12
	v_add_f32_dpp v9, v9, v9 row_half_mirror row_mask:0xf bank_mask:0xf bound_ctrl:1
	v_mov_b32_e32 v12, v1
	s_nop 0
	v_add_f32_dpp v9, v9, v9 row_mirror row_mask:0xf bank_mask:0xf bound_ctrl:1
	v_mov_b32_dpp v12, v11 row_bcast:31 row_mask:0xc bank_mask:0xf
	s_nop 0
	v_mov_b32_dpp v10, v9 row_bcast:15 row_mask:0xa bank_mask:0xf
	v_add_f32_e32 v9, v9, v10
	v_mov_b32_e32 v10, v1
	s_nop 1
	v_mov_b32_dpp v10, v9 row_bcast:31 row_mask:0xc bank_mask:0xf
	s_and_saveexec_b64 s[12:13], s[4:5]
	s_cbranch_execz .LBB0_310
	v_add_f32_e32 v11, v11, v12
	v_mul_f32_e32 v12, 0x4f800000, v11
	v_cmp_gt_f32_e32 vcc, s93, v11
	s_ashr_i32 s1, s0, 31
	v_add_f32_e32 v9, v9, v10
	v_cndmask_b32_e32 v11, v11, v12, vcc
	v_sqrt_f32_e32 v12, v11
	s_lshl_b64 s[0:1], s[0:1], 3
	s_add_u32 s0, s0, s48
	s_addc_u32 s1, s1, 0
	v_add_u32_e32 v13, -1, v12
	v_fma_f32 v15, -v13, v12, v11
	v_add_u32_e32 v14, 1, v12
	v_cmp_ge_f32_e64 s[10:11], 0, v15
	s_lshl_b64 s[0:1], s[0:1], 2
	s_mov_b32 s24, s53
	v_cndmask_b32_e64 v13, v12, v13, s[10:11]
	v_fma_f32 v12, -v14, v12, v11
	v_cmp_lt_f32_e64 s[10:11], 0, v12
	s_nop 1
	v_cndmask_b32_e64 v12, v13, v14, s[10:11]
	v_mul_f32_e32 v13, 0x37800000, v12
	v_cndmask_b32_e32 v12, v12, v13, vcc
	v_cmp_class_f32_e32 vcc, v11, v170
	s_nop 1
	v_cndmask_b32_e32 v11, v12, v11, vcc
	v_max_f32_e32 v11, 0x2b8cbccc, v11
	v_div_scale_f32 v12, s[10:11], v11, v11, 1.0
	v_rcp_f32_e32 v13, v12
	s_add_u32 s10, s28, s0
	s_addc_u32 s11, s29, s1
	s_add_u32 s0, s30, s0
	v_fma_f32 v10, -v12, v13, 1.0
	v_fmac_f32_e32 v13, v10, v13
	v_div_scale_f32 v10, vcc, 1.0, v11, 1.0
	v_mul_f32_e32 v14, v10, v13
	v_fma_f32 v15, -v12, v14, v10
	v_fmac_f32_e32 v14, v15, v13
	v_fma_f32 v10, -v12, v14, v10
	v_div_fmas_f32 v10, v10, v13, v14
	v_div_fixup_f32 v10, v10, v11, 1.0
	s_addc_u32 s1, s31, s1
	global_store_dword v1, v10, s[10:11]
	global_store_dword v1, v9, s[0:1]
